# v22 + nt on P6 epilogue loads, P4a chunk loads, P4c item loads
# speedup vs baseline: 1.0082x; 1.0043x over previous
; __device__ __forceinline__ float bf2f(bf16 v) { return __uint_as_float((unsigned)v << 16); }
; __device__ __forceinline__ void chunk_load(const PAArgs& A, int item, int wave, int lane, ChunkRaw& R) {
;     const bf16* Rr = (const bf16*)(A.ws + WS_R); const bf16* Kr = (const bf16*)(A.ws + WS_K); const bf16* Vr = (const bf16*)(A.ws + WS_V);
;     const bf16* AH = (const bf16*)(A.ws + WS_HBUF + 32 * MiB); const float* LW = (const float*)(A.ws + WS_LW);
;     const int bh = item >> 6, ck = item & 63;
; #pragma unroll
;     for (int i = 0; i < 8; ++i) {
;         const size_t o = ((size_t)bh * SEQ + ck * 64 + wave * 8 + i) * 64 + lane;
;         R.lwv[i] = LW[o]; R.rb[i] = Rr[o]; R.kb[i] = Kr[o]; R.vb[i] = Vr[o]; R.ab[i] = AH[o];
;     }
; }
; __device__ __forceinline__ void chunk_item(const PAArgs& A, unsigned char* lds, int item, int tid, int wave, int lane, const ChunkRaw& RAW) {
;     ...
;         float run = 0.f;
; #pragma unroll
;         for (int i = 0; i < 8; ++i) {
;             lwv[i] = RAW.lwv[i]; rv[i] = bf2f(RAW.rb[i]); kv[i] = bf2f(RAW.kb[i]); vb[i] = RAW.vb[i]; av[i] = bf2f(RAW.ab[i]);
;             run += lwv[i]; pl[i] = run;
;         }
;         CUMT[tg * 64 + ch] = run;
.LBB0_429:
	s_mov_b32 s12, s36
	s_add_i32 s36, s36, s30
	s_cmpk_gt_i32 s36, 0xfff
	s_cselect_b64 s[40:41], -1, 0
	s_cmpk_lt_i32 s36, 0x1000
	s_cselect_b32 s10, s36, s12
	s_ashr_i32 s6, s10, 6
	s_lshl_b32 s10, s10, 6
	s_and_b32 s10, s10, 0xfc0
	s_ashr_i32 s7, s6, 31
	s_add_i32 s48, s10, s35
	s_lshl_b64 s[6:7], s[6:7], 18
	s_lshl_b64 s[10:11], s[48:49], 6
	s_add_u32 s6, s6, s10
	s_addc_u32 s7, s7, s11
	v_lshl_add_u64 v[18:19], s[6:7], 0, v[8:9]
	v_mov_b32_e32 v144, v23
	v_mov_b32_e32 v120, v22
	v_lshlrev_b64 v[22:23], 1, v[18:19]
	v_mov_b32_e32 v141, v31
	s_waitcnt vmcnt(1)
	v_mov_b32_e32 v0, v25
	v_mov_b32_e32 v121, v26
	v_mov_b32_e32 v118, v24
	v_mov_b32_e32 v119, v28
	v_mov_b32_e32 v116, v27
	v_mov_b32_e32 v1, v30
	v_mov_b32_e32 v115, v29
	v_lshl_add_u64 v[24:25], s[42:43], 0, v[22:23]
	v_lshl_add_u64 v[26:27], s[44:45], 0, v[22:23]
	v_lshl_add_u64 v[28:29], s[70:71], 0, v[22:23]
	v_lshl_add_u64 v[30:31], s[46:47], 0, v[22:23]
	v_lshl_add_u64 v[22:23], v[18:19], 0, 64
	v_mov_b32_e32 v146, v36
	v_mov_b32_e32 v150, v37
	v_lshl_add_u64 v[20:21], v[18:19], 2, s[74:75]
	v_lshlrev_b64 v[36:37], 1, v[22:23]
	s_waitcnt vmcnt(0)
	v_mov_b32_e32 v140, v33
	v_mov_b32_e32 v142, v39
	v_mov_b32_e32 v143, v38
	v_mov_b32_e32 v147, v35
	v_mov_b32_e32 v148, v41
	v_mov_b32_e32 v149, v40
	v_mov_b32_e32 v117, v34
	v_lshl_add_u64 v[34:35], v[22:23], 2, s[74:75]
	v_lshl_add_u64 v[38:39], s[42:43], 0, v[36:37]
	v_lshl_add_u64 v[40:41], s[44:45], 0, v[36:37]
	global_load_dword v33, v[20:21], off nt
	s_nop 0
	global_load_ushort v25, v[24:25], off nt
	s_nop 0
	global_load_ushort v99, v[26:27], off nt
	global_load_ushort v22, v[28:29], off nt
	global_load_ushort v100, v[30:31], off nt
	s_nop 0
	global_load_dword v31, v[34:35], off nt
	global_load_ushort v23, v[38:39], off nt
	global_load_ushort v101, v[40:41], off nt
	v_lshl_add_u64 v[26:27], v[18:19], 0, s[68:69]
	v_lshl_add_u64 v[34:35], v[26:27], 2, s[74:75]
	v_lshlrev_b64 v[26:27], 1, v[26:27]
	s_mov_b64 s[0:1], 0xc0
	v_lshl_add_u64 v[20:21], s[70:71], 0, v[36:37]
	v_lshl_add_u64 v[28:29], s[46:47], 0, v[36:37]
	v_lshl_add_u64 v[36:37], s[42:43], 0, v[26:27]
	v_lshl_add_u64 v[106:107], v[18:19], 0, s[0:1]
	s_mov_b64 s[0:1], 0x100
	v_mov_b32_e32 v129, v42
	v_mov_b32_e32 v128, v45
	v_mov_b32_e32 v125, v44
	v_mov_b32_e32 v124, v43
	v_mov_b32_e32 v145, v32
	v_lshl_add_u64 v[40:41], s[44:45], 0, v[26:27]
	v_lshl_add_u64 v[42:43], s[70:71], 0, v[26:27]
	v_lshl_add_u64 v[44:45], s[46:47], 0, v[26:27]
	v_lshl_add_u64 v[108:109], v[106:107], 2, s[74:75]
	global_load_ushort v26, v[20:21], off nt
	global_load_ushort v102, v[28:29], off nt
	global_load_dword v39, v[34:35], off nt
	global_load_ushort v32, v[36:37], off nt
	global_load_ushort v103, v[40:41], off nt
	global_load_ushort v24, v[42:43], off nt
	global_load_ushort v104, v[44:45], off nt
	global_load_dword v38, v[108:109], off nt
	v_lshlrev_b64 v[20:21], 1, v[106:107]
	v_lshl_add_u64 v[36:37], v[18:19], 0, s[0:1]
	v_lshl_add_u64 v[28:29], s[42:43], 0, v[20:21]
	v_lshl_add_u64 v[34:35], s[44:45], 0, v[20:21]
	v_lshl_add_u64 v[40:41], s[70:71], 0, v[20:21]
	v_lshl_add_u64 v[42:43], v[36:37], 2, s[74:75]
	v_lshlrev_b64 v[44:45], 1, v[36:37]
	s_mov_b64 s[0:1], 0x140
	v_lshl_add_u64 v[20:21], s[46:47], 0, v[20:21]
	v_lshl_add_u64 v[108:109], s[42:43], 0, v[44:45]
	v_lshl_add_u64 v[110:111], s[44:45], 0, v[44:45]
	v_lshl_add_u64 v[112:113], s[70:71], 0, v[44:45]
	global_load_ushort v36, v[28:29], off nt
	global_load_ushort v105, v[34:35], off nt
	s_nop 0
	global_load_ushort v28, v[40:41], off nt
	global_load_ushort v106, v[20:21], off nt
	s_nop 0
	global_load_dword v42, v[42:43], off nt
	s_nop 0
	global_load_ushort v35, v[108:109], off nt
	global_load_ushort v107, v[110:111], off nt
	global_load_ushort v27, v[112:113], off nt
	v_lshl_add_u64 v[40:41], v[18:19], 0, s[0:1]
	v_lshl_add_u64 v[20:21], s[46:47], 0, v[44:45]
	v_lshl_add_u64 v[44:45], v[40:41], 2, s[74:75]
	v_lshlrev_b64 v[40:41], 1, v[40:41]
	s_mov_b64 s[0:1], 0x180
	v_lshl_add_u64 v[110:111], s[42:43], 0, v[40:41]
	v_lshl_add_u64 v[112:113], s[44:45], 0, v[40:41]
	v_lshl_add_u64 v[130:131], s[70:71], 0, v[40:41]
	v_lshl_add_u64 v[132:133], s[46:47], 0, v[40:41]
	v_lshl_add_u64 v[40:41], v[18:19], 0, s[0:1]
	s_mov_b64 s[0:1], 0x1c0
	v_lshlrev_b64 v[136:137], 1, v[40:41]
	v_lshl_add_u64 v[18:19], v[18:19], 0, s[0:1]
	v_lshl_add_u64 v[134:135], v[40:41], 2, s[74:75]
	v_lshl_add_u64 v[138:139], s[42:43], 0, v[136:137]
	global_load_ushort v108, v[20:21], off nt
	s_nop 0
	global_load_dword v45, v[44:45], off nt
	s_nop 0
	global_load_ushort v41, v[110:111], off nt
	global_load_ushort v109, v[112:113], off nt
	global_load_ushort v34, v[130:131], off nt
	s_nop 0
	global_load_ushort v110, v[132:133], off nt
	global_load_dword v44, v[134:135], off nt
	global_load_ushort v40, v[138:139], off nt
	v_lshl_add_u64 v[132:133], v[18:19], 2, s[74:75]
	v_lshlrev_b64 v[18:19], 1, v[18:19]
	v_lshl_add_u64 v[20:21], s[44:45], 0, v[136:137]
	v_lshl_add_u64 v[112:113], s[70:71], 0, v[136:137]
	v_lshl_add_u64 v[134:135], s[42:43], 0, v[18:19]
	v_lshl_add_u64 v[130:131], s[46:47], 0, v[136:137]
	v_lshl_add_u64 v[136:137], s[44:45], 0, v[18:19]
	v_lshl_add_u64 v[138:139], s[70:71], 0, v[18:19]
	v_lshl_add_u64 v[18:19], s[46:47], 0, v[18:19]
	global_load_ushort v111, v[20:21], off nt
	global_load_ushort v30, v[112:113], off nt
	s_nop 0
	global_load_ushort v112, v[130:131], off nt
	global_load_dword v43, v[132:133], off nt
	global_load_ushort v37, v[134:135], off nt
	global_load_ushort v113, v[136:137], off nt
	global_load_ushort v29, v[138:139], off nt
	global_load_ushort v114, v[18:19], off nt
	v_add_f32_e32 v134, 0, v140
	v_add_f32_e32 v135, v134, v141
	v_add_f32_e32 v138, v135, v142
	v_add_f32_e32 v139, v138, v143
	v_add_f32_e32 v151, v139, v129
	v_add_f32_e32 v152, v151, v128
	s_and_b32 s6, s12, 0x1c0
	v_add_f32_e32 v153, v152, v125
	v_add_u32_e32 v18, s6, v8
	v_add_f32_e32 v154, v153, v124
	v_ashrrev_i32_e32 v19, 31, v18
	v_readlane_b32 s0, v241, 32
	s_waitcnt lgkmcnt(0)
	s_barrier
; __device__ __forceinline__ unsigned f2bf(float f) { return pk2(f, f) & 0xffffu; }
; #define LBAR() do { asm volatile("s_waitcnt lgkmcnt(0)" ::: "memory"); __builtin_amdgcn_s_barrier(); asm volatile("" ::: "memory"); } while (0)
; __device__ __forceinline__ void chunk_item(const PAArgs& A, unsigned char* lds, int item, int tid, int wave, int lane, const ChunkRaw& RAW) {
;     ...
;         CUMT[tg * 64 + ch] = run;
;         LBAR();
;         float off = 0.f, tot = 0.f;
; #pragma unroll
;         for (int g = 0; g < 8; ++g) { const float c = CUMT[g * 64 + ch]; tot += c; off += (g < tg) ? c : 0.f; }
;         const float kkc = A.k_k[h * 64 + ch], kac = A.k_a[h * 64 + ch];
;         const float etot = __expf(tot);
;         unsigned bhp[4], khp[4], vp[4];
;         float bhv[8], khv[8], atv[8];
; #pragma unroll
;         for (int i = 0; i < 8; ++i) {
;             const float cl = off + pl[i], clp = cl - lwv[i];
;             const float kq = kv[i] * kkc;
;             const float kk = kq * __builtin_amdgcn_rsqf(fmaxf(wave_sum(kq * kq), 1e-24f));
;             const float a_ = -kk, b_ = kk * av[i], kp = kv[i] * (1.0f + (av[i] - 1.0f) * kac);
;             const float ecl = __expf(cl), encl = __builtin_amdgcn_rcpf(ecl), eclp = __expf(clp), eh = etot * encl;
;             const int tok = tg * 8 + i;
;             atv[i] = a_ * eclp; AT[tok * MST + ch] = (bf16)f2bf(a_ * eclp); BT[tok * MST + ch] = (bf16)f2bf(b_ * encl); KT[tok * MST + ch] = (bf16)f2bf(kp * encl); RT[tok * MST + ch] = (bf16)f2bf(rv[i] * ecl);
	ds_write_b32 v46, v154
	v_lshlrev_b64 v[18:19], 2, v[18:19]
	v_readlane_b32 s14, v241, 46
	v_readlane_b32 s15, v241, 47
	s_waitcnt lgkmcnt(0)
	s_barrier
	v_readlane_b32 s12, v241, 44
	v_lshl_add_u64 v[20:21], s[14:15], 0, v[18:19]
	global_load_dword v4, v[20:21], off nt
	v_readlane_b32 s13, v241, 45
	v_readlane_b32 s1, v241, 33
	v_readlane_b32 s0, v241, 61
	v_lshl_add_u64 v[18:19], s[12:13], 0, v[18:19]
	global_load_dword v2, v[18:19], off nt
	ds_read2st64_b32 v[18:19], v47 offset1:1
	v_lshlrev_b32_e32 v136, 16, v0
	ds_read2st64_b32 v[20:21], v47 offset0:2 offset1:3
	ds_read2st64_b32 v[130:131], v47 offset0:4 offset1:5
	ds_read2st64_b32 v[132:133], v47 offset0:6 offset1:7
	v_readlane_b32 s1, v241, 62
	v_lshlrev_b32_e32 v137, 16, v144
	s_waitcnt lgkmcnt(3)
	v_add_f32_e32 v0, 0, v18
	v_cndmask_b32_e64 v18, v0, 0, s[38:39]
	v_add_f32_e32 v0, v0, v19
	v_cndmask_b32_e64 v19, 0, v19, s[0:1]
	v_readlane_b32 s0, v241, 63
	v_readlane_b32 s1, v240, 0
	v_add_f32_e32 v18, v18, v19
	v_lshlrev_b32_e32 v144, 16, v145
	s_waitcnt lgkmcnt(2)
	v_cndmask_b32_e64 v19, 0, v20, s[0:1]
	v_readlane_b32 s0, v240, 6
	v_readlane_b32 s1, v240, 7
	v_add_f32_e32 v18, v18, v19
	v_lshlrev_b32_e32 v145, 16, v146
	v_cndmask_b32_e64 v19, 0, v21, s[0:1]
	v_readlane_b32 s0, v240, 8
	v_readlane_b32 s1, v240, 9
	v_add_f32_e32 v18, v18, v19
	v_lshlrev_b32_e32 v146, 16, v147
	s_waitcnt lgkmcnt(1)
	v_cndmask_b32_e64 v19, 0, v130, s[0:1]
	v_readlane_b32 s0, v240, 10
	v_readlane_b32 s1, v240, 11
	v_add_f32_e32 v18, v18, v19
	v_lshlrev_b32_e32 v147, 16, v148
	v_cndmask_b32_e64 v19, 0, v131, s[0:1]
	v_readlane_b32 s0, v240, 12
	v_readlane_b32 s1, v240, 13
	v_add_f32_e32 v18, v18, v19
	v_lshlrev_b32_e32 v148, 16, v149
	s_waitcnt lgkmcnt(0)
	v_cndmask_b32_e64 v19, 0, v132, s[0:1]
	v_readlane_b32 s0, v240, 14
	v_readlane_b32 s1, v240, 15
	v_add_f32_e32 v18, v18, v19
	v_lshlrev_b32_e32 v149, 16, v150
	v_cndmask_b32_e64 v19, 0, v133, s[0:1]
	v_add_f32_e32 v150, v18, v19
	v_add_f32_e32 v18, v134, v150
	v_add_f32_e32 v0, v0, v20
	v_mul_f32_e32 v19, 0x3fb8aa3b, v18
	v_add_f32_e32 v0, v0, v21
	v_exp_f32_e32 v19, v19
	v_add_f32_e32 v21, v135, v150
	v_add_f32_e32 v0, v0, v130
	v_mul_f32_e32 v130, 0x3fb8aa3b, v21
	v_exp_f32_e32 v130, v130
	v_sub_f32_e32 v20, v18, v140
	v_rcp_f32_e32 v18, v19
	v_mul_f32_e32 v19, v19, v136
	v_cvt_pk_bf16_f32 v19, v19, s0
	v_add_f32_e32 v0, v0, v131
	ds_write_b16 v48, v19 offset:27648
	v_rcp_f32_e32 v19, v130
	v_mul_f32_e32 v130, v130, v137
	v_add_f32_e32 v0, v0, v132
	v_cvt_pk_bf16_f32 v140, v130, s0
	v_and_b32_e32 v131, 0xffff0000, v7
	v_lshlrev_b32_e32 v130, 16, v7
	v_and_b32_e32 v7, 0xffff0000, v6
	v_lshlrev_b32_e32 v6, 16, v6
	v_add_f32_e32 v0, v0, v133
	v_pk_add_f32 v[132:133], v[6:7], -1.0 op_sel_hi:[1,0]
	v_mov_b32_e32 v136, 0
	v_readlane_b32 s6, v241, 38
	v_sub_f32_e32 v21, v21, v141
	v_mul_f32_e32 v20, 0x3fb8aa3b, v20
	v_mul_f32_e32 v21, 0x3fb8aa3b, v21
	v_mul_f32_e32 v0, 0x3fb8aa3b, v0
	v_exp_f32_e32 v20, v20
	v_exp_f32_e32 v21, v21
	v_exp_f32_e32 v0, v0
	s_waitcnt vmcnt(1)
	v_pk_fma_f32 v[132:133], v[132:133], v[4:5], 1.0 op_sel_hi:[1,0,0]
	v_lshlrev_b32_e32 v115, 16, v115
	v_pk_mul_f32 v[132:133], v[132:133], v[130:131]
	v_readlane_b32 s7, v241, 39
	v_mul_f32_e32 v134, v132, v18
	v_cvt_pk_bf16_f32 v134, v134, s0
	s_waitcnt vmcnt(0)
	v_pk_mul_f32 v[130:131], v[2:3], v[130:131] op_sel_hi:[0,1]
	ds_write_b16 v48, v134 offset:18432
	v_pk_mul_f32 v[134:135], v[130:131], v[130:131]
	v_mul_f32_e32 v141, v133, v19
	v_cvt_pk_bf16_f32 v141, v141, s0
	v_add_f32_dpp v134, v134, v134 quad_perm:[1,0,3,2] row_mask:0xf bank_mask:0xf bound_ctrl:1
	v_add_f32_dpp v135, v135, v135 quad_perm:[1,0,3,2] row_mask:0xf bank_mask:0xf bound_ctrl:1
	s_andn2_b64 vcc, exec, s[38:39]
	v_add_f32_dpp v134, v134, v134 quad_perm:[2,3,0,1] row_mask:0xf bank_mask:0xf bound_ctrl:1
	v_add_f32_dpp v135, v135, v135 quad_perm:[2,3,0,1] row_mask:0xf bank_mask:0xf bound_ctrl:1
	v_readlane_b32 s2, v241, 34
	v_add_f32_dpp v134, v134, v134 row_half_mirror row_mask:0xf bank_mask:0xf bound_ctrl:1
	v_add_f32_dpp v135, v135, v135 row_half_mirror row_mask:0xf bank_mask:0xf bound_ctrl:1
	v_readlane_b32 s3, v241, 35
	v_add_f32_dpp v134, v134, v134 row_mirror row_mask:0xf bank_mask:0xf bound_ctrl:1
	v_add_f32_dpp v135, v135, v135 row_mirror row_mask:0xf bank_mask:0xf bound_ctrl:1
	v_readlane_b32 s4, v241, 36
	v_mov_b32_dpp v136, v134 row_bcast:15 row_mask:0xa bank_mask:0xf
	v_add_f32_e32 v134, v134, v136
	v_mov_b32_e32 v136, 0
	v_readlane_b32 s5, v241, 37
	v_readlane_b32 s8, v241, 40
	v_mov_b32_dpp v136, v134 row_bcast:31 row_mask:0xc bank_mask:0xf
	v_add_f32_e32 v134, v134, v136
	v_mov_b32_e32 v136, 0
	v_readlane_b32 s6, v134, 63
	v_readlane_b32 s9, v241, 41
	v_mov_b32_dpp v136, v135 row_bcast:15 row_mask:0xa bank_mask:0xf
	v_add_f32_e32 v135, v135, v136
	v_mov_b32_e32 v136, 0
	v_max_f32_e64 v134, s6, s6
	v_max_f32_e32 v134, 0x179abe15, v134
	v_mov_b32_dpp v136, v135 row_bcast:31 row_mask:0xc bank_mask:0xf
	v_add_f32_e32 v135, v135, v136
	v_rsq_f32_e32 v134, v134
	v_readlane_b32 s6, v135, 63
	v_pk_mul_f32 v[136:137], v[0:1], v[18:19] op_sel_hi:[0,1]
	v_readlane_b32 s10, v241, 42
	v_max_f32_e64 v135, s6, s6
	v_max_f32_e32 v135, 0x179abe15, v135
	v_rsq_f32_e32 v135, v135
	v_readlane_b32 s11, v241, 43
	v_pk_mul_f32 v[130:131], v[130:131], v[134:135]
	s_nop 0
	v_pk_mul_f32 v[134:135], v[130:131], v[6:7]
	s_nop 0
	v_mul_f32_e32 v6, v18, v134
	v_cvt_pk_bf16_f32 v6, v6, s0
	ds_write_b16 v48, v6 offset:9216
	v_pk_mul_f32 v[6:7], v[20:21], v[130:131] neg_lo:[0,1] neg_hi:[0,1]
	v_add_f32_e32 v130, v138, v150
	v_cvt_pk_bf16_f32 v18, v6, s0
	ds_write_b16 v48, v18
	v_cvt_pk_bf16_f32 v18, v7, s0
	ds_write_b16 v48, v18 offset:144
; __device__ __forceinline__ unsigned f2bf(float f) { return pk2(f, f) & 0xffffu; }
; __device__ __forceinline__ void chunk_item(const PAArgs& A, unsigned char* lds, int item, int tid, int wave, int lane, const ChunkRaw& RAW) {
;     ...
;         for (int i = 0; i < 8; ++i) {
;             const float cl = off + pl[i], clp = cl - lwv[i];
;             const float kq = kv[i] * kkc;
;             const float kk = kq * __builtin_amdgcn_rsqf(fmaxf(wave_sum(kq * kq), 1e-24f));
;             const float a_ = -kk, b_ = kk * av[i], kp = kv[i] * (1.0f + (av[i] - 1.0f) * kac);
;             const float ecl = __expf(cl), encl = __builtin_amdgcn_rcpf(ecl), eclp = __expf(clp), eh = etot * encl;
;             const int tok = tg * 8 + i;
;             atv[i] = a_ * eclp; AT[tok * MST + ch] = (bf16)f2bf(a_ * eclp); BT[tok * MST + ch] = (bf16)f2bf(b_ * encl); KT[tok * MST + ch] = (bf16)f2bf(kp * encl); RT[tok * MST + ch] = (bf16)f2bf(rv[i] * ecl);
;             bhv[i] = b_ * eh; khv[i] = kp * eh;
;         }
	v_mul_f32_e32 v18, v19, v135
	v_cvt_pk_bf16_f32 v18, v18, s0
	ds_write_b16 v48, v18 offset:9360
	ds_write_b16 v48, v141 offset:18576
	ds_write_b16 v48, v140 offset:27792
	v_mul_f32_e32 v18, 0x3fb8aa3b, v130
	v_exp_f32_e32 v131, v18
	v_pk_mul_f32 v[20:21], v[132:133], v[136:137]
	v_add_f32_e32 v133, v139, v150
	v_pk_mul_f32 v[18:19], v[136:137], v[134:135]
	v_mul_f32_e32 v134, 0x3fb8aa3b, v133
	v_exp_f32_e32 v134, v134
	v_sub_f32_e32 v132, v130, v142
	v_rcp_f32_e32 v130, v131
	v_mul_f32_e32 v131, v131, v144
	v_cvt_pk_bf16_f32 v131, v131, s0
	ds_write_b16 v48, v131 offset:27936
	v_rcp_f32_e32 v131, v134
	v_mul_f32_e32 v134, v134, v145
	v_cvt_pk_bf16_f32 v142, v134, s0
	v_and_b32_e32 v135, 0xffff0000, v127
	v_lshlrev_b32_e32 v134, 16, v127
	v_and_b32_e32 v127, 0xffff0000, v126
	v_lshlrev_b32_e32 v126, 16, v126
	v_pk_add_f32 v[136:137], v[126:127], -1.0 op_sel_hi:[1,0]
	v_mov_b32_e32 v140, 0
	v_pk_fma_f32 v[136:137], v[136:137], v[4:5], 1.0 op_sel_hi:[1,0,0]
	v_sub_f32_e32 v133, v133, v143
	v_pk_mul_f32 v[136:137], v[136:137], v[134:135]
	v_pk_mul_f32 v[134:135], v[2:3], v[134:135] op_sel_hi:[0,1]
	v_mul_f32_e32 v138, v136, v130
	v_cvt_pk_bf16_f32 v138, v138, s0
	ds_write_b16 v48, v138 offset:18720
	v_pk_mul_f32 v[138:139], v[134:135], v[134:135]
	v_mul_f32_e32 v132, 0x3fb8aa3b, v132
	v_mul_f32_e32 v133, 0x3fb8aa3b, v133
	v_add_f32_dpp v138, v138, v138 quad_perm:[1,0,3,2] row_mask:0xf bank_mask:0xf bound_ctrl:1
	v_add_f32_dpp v139, v139, v139 quad_perm:[1,0,3,2] row_mask:0xf bank_mask:0xf bound_ctrl:1
	v_exp_f32_e32 v132, v132
	v_add_f32_dpp v138, v138, v138 quad_perm:[2,3,0,1] row_mask:0xf bank_mask:0xf bound_ctrl:1
	v_add_f32_dpp v139, v139, v139 quad_perm:[2,3,0,1] row_mask:0xf bank_mask:0xf bound_ctrl:1
	v_exp_f32_e32 v133, v133
	v_add_f32_dpp v138, v138, v138 row_half_mirror row_mask:0xf bank_mask:0xf bound_ctrl:1
	v_add_f32_dpp v139, v139, v139 row_half_mirror row_mask:0xf bank_mask:0xf bound_ctrl:1
	v_mul_f32_e32 v143, v137, v131
	v_add_f32_dpp v138, v138, v138 row_mirror row_mask:0xf bank_mask:0xf bound_ctrl:1
	v_add_f32_dpp v139, v139, v139 row_mirror row_mask:0xf bank_mask:0xf bound_ctrl:1
	v_cvt_pk_bf16_f32 v143, v143, s0
	v_mov_b32_dpp v140, v138 row_bcast:15 row_mask:0xa bank_mask:0xf
	v_add_f32_e32 v138, v138, v140
	v_mov_b32_e32 v140, 0
	s_nop 1
	v_mov_b32_dpp v140, v138 row_bcast:31 row_mask:0xc bank_mask:0xf
	v_add_f32_e32 v138, v138, v140
	v_mov_b32_e32 v140, 0
	v_readlane_b32 s6, v138, 63
	s_nop 0
	v_mov_b32_dpp v140, v139 row_bcast:15 row_mask:0xa bank_mask:0xf
	v_add_f32_e32 v139, v139, v140
	v_mov_b32_e32 v140, 0
	v_max_f32_e64 v138, s6, s6
	v_max_f32_e32 v138, 0x179abe15, v138
	v_mov_b32_dpp v140, v139 row_bcast:31 row_mask:0xc bank_mask:0xf
	v_add_f32_e32 v139, v139, v140
	v_rsq_f32_e32 v138, v138
	v_readlane_b32 s6, v139, 63
	v_pk_mul_f32 v[140:141], v[0:1], v[130:131] op_sel_hi:[0,1]
	s_nop 0
	v_max_f32_e64 v139, s6, s6
	v_max_f32_e32 v139, 0x179abe15, v139
	v_rsq_f32_e32 v139, v139
	s_nop 0
	v_pk_mul_f32 v[134:135], v[134:135], v[138:139]
	s_nop 0
	v_pk_mul_f32 v[126:127], v[134:135], v[126:127]
	v_pk_mul_f32 v[132:133], v[132:133], v[134:135] neg_lo:[0,1] neg_hi:[0,1]
	v_mul_f32_e32 v130, v130, v126
	v_cvt_pk_bf16_f32 v130, v130, s0
	ds_write_b16 v48, v130 offset:9504
	v_cvt_pk_bf16_f32 v130, v132, s0
	ds_write_b16 v48, v130 offset:288
	v_cvt_pk_bf16_f32 v130, v133, s0
	ds_write_b16 v48, v130 offset:432
	v_mul_f32_e32 v130, v131, v127
	v_cvt_pk_bf16_f32 v130, v130, s0
	v_add_f32_e32 v134, v151, v150
	ds_write_b16 v48, v130 offset:9648
	ds_write_b16 v48, v143 offset:18864
	ds_write_b16 v48, v142 offset:28080
	v_mul_f32_e32 v130, 0x3fb8aa3b, v134
	v_exp_f32_e32 v135, v130
	v_sub_f32_e32 v129, v134, v129
	v_mul_f32_e32 v129, 0x3fb8aa3b, v129
	v_pk_mul_f32 v[130:131], v[136:137], v[140:141]
	v_rcp_f32_e32 v134, v135
	v_exp_f32_e32 v136, v129
	v_mul_f32_e32 v129, v135, v146
	v_add_f32_e32 v135, v152, v150
	v_mul_f32_e32 v137, 0x3fb8aa3b, v135
	v_exp_f32_e32 v138, v137
	v_sub_f32_e32 v128, v135, v128
	v_mul_f32_e32 v128, 0x3fb8aa3b, v128
	v_cvt_pk_bf16_f32 v129, v129, s0
	v_exp_f32_e32 v137, v128
	v_mul_f32_e32 v128, v138, v147
	ds_write_b16 v48, v129 offset:28224
	v_cvt_pk_bf16_f32 v144, v128, s0
	v_and_b32_e32 v129, 0xffff0000, v123
	v_lshlrev_b32_e32 v128, 16, v123
	v_and_b32_e32 v123, 0xffff0000, v122
	v_lshlrev_b32_e32 v122, 16, v122
	v_rcp_f32_e32 v135, v138
	v_pk_add_f32 v[138:139], v[122:123], -1.0 op_sel_hi:[1,0]
	v_pk_mul_f32 v[126:127], v[140:141], v[126:127]
	v_pk_fma_f32 v[138:139], v[138:139], v[4:5], 1.0 op_sel_hi:[1,0,0]
	v_mov_b32_e32 v142, 0
	v_pk_mul_f32 v[138:139], v[138:139], v[128:129]
	v_pk_mul_f32 v[128:129], v[2:3], v[128:129] op_sel_hi:[0,1]
	v_mul_f32_e32 v140, v138, v134
	v_cvt_pk_bf16_f32 v140, v140, s0
	ds_write_b16 v48, v140 offset:19008
	v_pk_mul_f32 v[140:141], v[128:129], v[128:129]
	v_mul_f32_e32 v145, v139, v135
	v_cvt_pk_bf16_f32 v145, v145, s0
	v_add_f32_dpp v140, v140, v140 quad_perm:[1,0,3,2] row_mask:0xf bank_mask:0xf bound_ctrl:1
	v_add_f32_dpp v141, v141, v141 quad_perm:[1,0,3,2] row_mask:0xf bank_mask:0xf bound_ctrl:1
	s_nop 0
	v_add_f32_dpp v140, v140, v140 quad_perm:[2,3,0,1] row_mask:0xf bank_mask:0xf bound_ctrl:1
	v_add_f32_dpp v141, v141, v141 quad_perm:[2,3,0,1] row_mask:0xf bank_mask:0xf bound_ctrl:1
	s_nop 0
	v_add_f32_dpp v140, v140, v140 row_half_mirror row_mask:0xf bank_mask:0xf bound_ctrl:1
	v_add_f32_dpp v141, v141, v141 row_half_mirror row_mask:0xf bank_mask:0xf bound_ctrl:1
	s_nop 0
	v_add_f32_dpp v140, v140, v140 row_mirror row_mask:0xf bank_mask:0xf bound_ctrl:1
	v_add_f32_dpp v141, v141, v141 row_mirror row_mask:0xf bank_mask:0xf bound_ctrl:1
	s_nop 0
; __device__ __forceinline__ unsigned pk2(float lo, float hi) { f32x2_t v = {lo, hi}; bf16x2_t b = __builtin_convertvector(v, bf16x2_t); return __builtin_bit_cast(unsigned, b); }
; __device__ __forceinline__ unsigned f2bf(float f) { return pk2(f, f) & 0xffffu; }
; __device__ __forceinline__ void chunk_item(const PAArgs& A, unsigned char* lds, int item, int tid, int wave, int lane, const ChunkRaw& RAW) {
;     ...
;         for (int i = 0; i < 8; ++i) {
;             const float cl = off + pl[i], clp = cl - lwv[i];
;             const float kq = kv[i] * kkc;
;             const float kk = kq * __builtin_amdgcn_rsqf(fmaxf(wave_sum(kq * kq), 1e-24f));
;             const float a_ = -kk, b_ = kk * av[i], kp = kv[i] * (1.0f + (av[i] - 1.0f) * kac);
;             const float ecl = __expf(cl), encl = __builtin_amdgcn_rcpf(ecl), eclp = __expf(clp), eh = etot * encl;
;             const int tok = tg * 8 + i;
;             atv[i] = a_ * eclp; AT[tok * MST + ch] = (bf16)f2bf(a_ * eclp); BT[tok * MST + ch] = (bf16)f2bf(b_ * encl); KT[tok * MST + ch] = (bf16)f2bf(kp * encl); RT[tok * MST + ch] = (bf16)f2bf(rv[i] * ecl);
;             bhv[i] = b_ * eh; khv[i] = kp * eh;
;         }
; #pragma unroll
;         for (int i = 0; i < 4; ++i) { bhp[i] = pk2(bhv[2 * i], bhv[2 * i + 1]); khp[i] = pk2(khv[2 * i], khv[2 * i + 1]); vp[i] = (unsigned)vb[2 * i] | ((unsigned)vb[2 * i + 1] << 16); }
;         *(u32x4*)(BHT + ch * MST + tg * 8) = (u32x4){bhp[0], bhp[1], bhp[2], bhp[3]};
;         *(u32x4*)(KHT + ch * MST + tg * 8) = (u32x4){khp[0], khp[1], khp[2], khp[3]};
;         *(u32x4*)(VT + ch * MST + tg * 8) = (u32x4){vp[0], vp[1], vp[2], vp[3]};
;         *(u32x4*)(ATT + ch * MST + tg * 8) = (u32x4){pk2(atv[0], atv[1]), pk2(atv[2], atv[3]), pk2(atv[4], atv[5]), pk2(atv[6], atv[7])};
;         if (tg == 0) WCs[ch] = etot;
	v_mov_b32_dpp v142, v140 row_bcast:15 row_mask:0xa bank_mask:0xf
	v_add_f32_e32 v140, v140, v142
	v_mov_b32_e32 v142, 0
	s_nop 1
	v_mov_b32_dpp v142, v140 row_bcast:31 row_mask:0xc bank_mask:0xf
	v_add_f32_e32 v140, v140, v142
	v_mov_b32_e32 v142, 0
	v_readlane_b32 s6, v140, 63
	s_nop 0
	v_mov_b32_dpp v142, v141 row_bcast:15 row_mask:0xa bank_mask:0xf
	v_add_f32_e32 v141, v141, v142
	v_mov_b32_e32 v142, 0
	v_max_f32_e64 v140, s6, s6
	v_max_f32_e32 v140, 0x179abe15, v140
	v_mov_b32_dpp v142, v141 row_bcast:31 row_mask:0xc bank_mask:0xf
	v_add_f32_e32 v141, v141, v142
	v_rsq_f32_e32 v140, v140
	v_readlane_b32 s6, v141, 63
	v_pk_mul_f32 v[142:143], v[0:1], v[134:135] op_sel_hi:[0,1]
	s_nop 0
	v_max_f32_e64 v141, s6, s6
	v_max_f32_e32 v141, 0x179abe15, v141
	v_rsq_f32_e32 v141, v141
	s_nop 0
	v_pk_mul_f32 v[128:129], v[128:129], v[140:141]
	s_nop 0
	v_pk_mul_f32 v[122:123], v[128:129], v[122:123]
	v_pk_mul_f32 v[128:129], v[136:137], v[128:129] neg_lo:[0,1] neg_hi:[0,1]
	v_mul_f32_e32 v134, v134, v122
	v_cvt_pk_bf16_f32 v134, v134, s0
	ds_write_b16 v48, v134 offset:9792
	v_cvt_pk_bf16_f32 v134, v128, s0
	ds_write_b16 v48, v134 offset:576
	v_cvt_pk_bf16_f32 v134, v129, s0
	ds_write_b16 v48, v134 offset:720
	v_mul_f32_e32 v134, v135, v123
	v_cvt_pk_bf16_f32 v134, v134, s0
	v_add_f32_e32 v136, v153, v150
	ds_write_b16 v48, v134 offset:9936
	ds_write_b16 v48, v145 offset:19152
	ds_write_b16 v48, v144 offset:28368
	v_mul_f32_e32 v134, 0x3fb8aa3b, v136
	v_exp_f32_e32 v137, v134
	v_sub_f32_e32 v125, v136, v125
	v_mul_f32_e32 v125, 0x3fb8aa3b, v125
	v_pk_mul_f32 v[134:135], v[138:139], v[142:143]
	v_rcp_f32_e32 v136, v137
	v_exp_f32_e32 v138, v125
	v_mul_f32_e32 v125, v137, v148
	v_add_f32_e32 v137, v154, v150
	v_mul_f32_e32 v139, 0x3fb8aa3b, v137
	v_exp_f32_e32 v140, v139
	v_sub_f32_e32 v124, v137, v124
	v_mul_f32_e32 v124, 0x3fb8aa3b, v124
	v_exp_f32_e32 v139, v124
	v_rcp_f32_e32 v137, v140
	v_mul_f32_e32 v124, v140, v149
	v_and_b32_e32 v141, 0xffff0000, v3
	v_lshlrev_b32_e32 v140, 16, v3
	v_pk_mul_f32 v[122:123], v[142:143], v[122:123]
	v_cvt_pk_bf16_f32 v125, v125, s0
	v_pk_add_f32 v[142:143], v[140:141], -1.0 op_sel_hi:[1,0]
	ds_write_b16 v48, v125 offset:28512
	v_cvt_pk_bf16_f32 v144, v124, s0
	v_and_b32_e32 v125, 0xffff0000, v5
	v_lshlrev_b32_e32 v124, 16, v5
	v_pk_fma_f32 v[4:5], v[142:143], v[4:5], 1.0 op_sel_hi:[1,0,0]
	v_mov_b32_e32 v142, 0
	v_pk_mul_f32 v[4:5], v[4:5], v[124:125]
	s_nop 0
	v_mul_f32_e32 v3, v4, v136
	v_cvt_pk_bf16_f32 v3, v3, s0
	ds_write_b16 v48, v3 offset:19296
	v_pk_mul_f32 v[2:3], v[2:3], v[124:125] op_sel_hi:[0,1]
	v_pk_mul_f32 v[124:125], v[2:3], v[2:3]
	v_mul_f32_e32 v145, v5, v137
	v_cvt_pk_bf16_f32 v145, v145, s0
	v_add_f32_dpp v124, v124, v124 quad_perm:[1,0,3,2] row_mask:0xf bank_mask:0xf bound_ctrl:1
	v_add_f32_dpp v125, v125, v125 quad_perm:[1,0,3,2] row_mask:0xf bank_mask:0xf bound_ctrl:1
	s_nop 0
	v_add_f32_dpp v124, v124, v124 quad_perm:[2,3,0,1] row_mask:0xf bank_mask:0xf bound_ctrl:1
	v_add_f32_dpp v125, v125, v125 quad_perm:[2,3,0,1] row_mask:0xf bank_mask:0xf bound_ctrl:1
	s_nop 0
	v_add_f32_dpp v124, v124, v124 row_half_mirror row_mask:0xf bank_mask:0xf bound_ctrl:1
	v_add_f32_dpp v125, v125, v125 row_half_mirror row_mask:0xf bank_mask:0xf bound_ctrl:1
	s_nop 0
	v_add_f32_dpp v124, v124, v124 row_mirror row_mask:0xf bank_mask:0xf bound_ctrl:1
	v_add_f32_dpp v125, v125, v125 row_mirror row_mask:0xf bank_mask:0xf bound_ctrl:1
	s_nop 0
	v_mov_b32_dpp v142, v124 row_bcast:15 row_mask:0xa bank_mask:0xf
	v_add_f32_e32 v124, v124, v142
	v_mov_b32_e32 v142, 0
	s_nop 1
	v_mov_b32_dpp v142, v124 row_bcast:31 row_mask:0xc bank_mask:0xf
	v_add_f32_e32 v124, v124, v142
	v_mov_b32_e32 v142, 0
	v_readlane_b32 s6, v124, 63
	s_nop 0
	v_mov_b32_dpp v142, v125 row_bcast:15 row_mask:0xa bank_mask:0xf
	v_add_f32_e32 v125, v125, v142
	v_mov_b32_e32 v142, 0
	v_max_f32_e64 v124, s6, s6
	v_max_f32_e32 v124, 0x179abe15, v124
	v_mov_b32_dpp v142, v125 row_bcast:31 row_mask:0xc bank_mask:0xf
	v_add_f32_e32 v125, v125, v142
	v_rsq_f32_e32 v124, v124
	v_readlane_b32 s6, v125, 63
	v_pk_mul_f32 v[142:143], v[0:1], v[136:137] op_sel_hi:[0,1]
	s_nop 0
	v_max_f32_e64 v125, s6, s6
	v_max_f32_e32 v125, 0x179abe15, v125
	v_rsq_f32_e32 v125, v125
	s_nop 0
	v_pk_mul_f32 v[2:3], v[2:3], v[124:125]
	s_nop 0
	v_pk_mul_f32 v[138:139], v[138:139], v[2:3] neg_lo:[0,1] neg_hi:[0,1]
	v_pk_mul_f32 v[124:125], v[2:3], v[140:141]
	v_cvt_pk_bf16_f32 v2, v138, s0
	v_mul_f32_e32 v136, v136, v124
	ds_write_b16 v48, v2 offset:864
	v_cvt_pk_bf16_f32 v2, v139, s0
	v_cvt_pk_bf16_f32 v136, v136, s0
	ds_write_b16 v48, v2 offset:1008
	v_mul_f32_e32 v2, v137, v125
	ds_write_b16 v48, v136 offset:10080
	v_cvt_pk_bf16_f32 v2, v2, s0
	v_pk_mul_f32 v[124:125], v[142:143], v[124:125]
	v_pk_mul_f32 v[136:137], v[4:5], v[142:143]
	v_lshlrev_b32_e32 v3, 16, v121
	v_lshlrev_b32_e32 v4, 16, v119
	v_lshlrev_b32_e32 v5, 16, v117
	ds_write_b16 v48, v2 offset:10224
	ds_write_b16 v48, v145 offset:19440
	ds_write_b16 v48, v144 offset:28656
	v_cvt_pk_bf16_f32 v2, v18, v19
	v_or_b32_sdwa v120, v3, v120 dst_sel:DWORD dst_unused:UNUSED_PAD src0_sel:DWORD src1_sel:WORD_0
	v_cvt_pk_bf16_f32 v3, v126, v127
	v_or_b32_sdwa v121, v4, v118 dst_sel:DWORD dst_unused:UNUSED_PAD src0_sel:DWORD src1_sel:WORD_0
	v_cvt_pk_bf16_f32 v4, v122, v123
	v_or_b32_sdwa v122, v5, v116 dst_sel:DWORD dst_unused:UNUSED_PAD src0_sel:DWORD src1_sel:WORD_0
	v_cvt_pk_bf16_f32 v5, v124, v125
	v_or_b32_sdwa v123, v115, v1 dst_sel:DWORD dst_unused:UNUSED_PAD src0_sel:DWORD src1_sel:WORD_0
	v_cndmask_b32_e64 v1, 0, 1, s[38:39]
	v_cvt_pk_bf16_f32 v18, v20, v21
	v_cvt_pk_bf16_f32 v19, v130, v131
	v_cvt_pk_bf16_f32 v20, v134, v135
	v_cvt_pk_bf16_f32 v21, v136, v137
	ds_write_b128 v49, v[2:5] offset:36864
	ds_write_b128 v49, v[18:21] offset:46080
	ds_write_b128 v49, v[120:123] offset:55296
	v_cvt_pk_bf16_f32 v2, v6, v7
	v_cvt_pk_bf16_f32 v3, v132, v133
	v_cvt_pk_bf16_f32 v4, v128, v129
	v_cvt_pk_bf16_f32 v5, v138, v139
	v_cmp_ne_u32_e64 s[6:7], 1, v1
	ds_write_b128 v50, v[2:5]
	s_cbranch_vccnz .LBB0_431
	ds_write_b32 v51, v0

; __device__ __forceinline__ void chunk_out(const PBArgs& A, unsigned char* lds, int G_, int wave, int lane) {
;     ...
;     const int it0 = blockIdx.x * 2 + half;
;     if (it0 < 4096) CO_LOAD(it0);
;     for (int it = it0; it < 4096; it += 2 * G_) {
;         const int bh = it >> 6, ck = it & 63, b = bh >> 3, h = bh & 7;
;         bf16x8 bR[2], aM[4][2]; u32x2 y0[4], vv[4], gg[4]; u32x4 rv[2], rg[2];
; #pragma unroll
;         for (int ks = 0; ks < 2; ++ks) bR[ks] = nbR[ks];
; #pragma unroll
;         for (int vi = 0; vi < 4; ++vi) { aM[vi][0] = naM[vi][0]; aM[vi][1] = naM[vi][1]; y0[vi] = ny0[vi]; }
; #pragma unroll
;         for (int j = 0; j < 2; ++j) { rv[j] = nrv[j]; rg[j] = nrg[j]; }
;         const float rk = (nr4[0] + nr4[1]) + (nr4[2] + nr4[3]);
;         {
; #pragma unroll
;             for (int j = 0; j < 2; ++j) { const int tk = (lane >> 3) + 8 * j, c16 = lane & 7; *(u32x4*)(ostg + tk * 144 + c16 * 16) = rv[j]; }
;             LDS_WAIT();
; #pragma unroll
;             for (int vi = 0; vi < 4; ++vi) vv[vi] = *(const u32x2*)(ostg + fr * 144 + (vi * 16 + fq * 4) * 2);
;             LDS_WAIT();
; #pragma unroll
;             for (int j = 0; j < 2; ++j) { const int tk = (lane >> 3) + 8 * j, c16 = lane & 7; *(u32x4*)(ostg + tk * 144 + c16 * 16) = rg[j]; }
;             LDS_WAIT();
; #pragma unroll
;             for (int vi = 0; vi < 4; ++vi) gg[vi] = *(const u32x2*)(ostg + fr * 144 + (vi * 16 + fq * 4) * 2);
;             LDS_WAIT();
;         }
;         f32x4 c[4];
; #pragma unroll
;         for (int vi = 0; vi < 4; ++vi) {
;             c[vi] = bf4(y0[vi]);
; #pragma unroll
;             for (int ks = 0; ks < 2; ++ks) c[vi] = __builtin_amdgcn_mfma_f32_16x16x32_bf16(aM[vi][ks], bR[ks], c[vi], 0, 0, 0);
;         }
;         { const int itn = (it + 2 * G_ < 4096) ? it + 2 * G_ : it; CO_LOAD(itn); }
;         float sm = 0.f;
; #pragma unroll
;         for (int vi = 0; vi < 4; ++vi) sm += (c[vi][0] + c[vi][1]) + (c[vi][2] + c[vi][3]);
;         sm = rows4_sum(sm);
;         const float mu = sm * (1.0f / 64.0f);
;         float q = 0.f;
; #pragma unroll
;         for (int vi = 0; vi < 4; ++vi) { c[vi] = c[vi] - mu; q += (c[vi][0] * c[vi][0] + c[vi][1] * c[vi][1]) + (c[vi][2] * c[vi][2] + c[vi][3] * c[vi][3]); }
;         q = rows4_sum(q);
;         const float rs = rsqrtf(q * (1.0f / 64.0f) + 64e-5f);
.LBB0_577:
	s_waitcnt vmcnt(4)
	v_add_u32_e32 v167, s99, v166
	ds_write_b128 v167, v[160:163]
	ds_write_b128 v167, v[174:177] offset:4096
	ds_write_b128 v93, v[44:47]
	s_waitcnt vmcnt(2)
	ds_write_b128 v93, v[52:55] offset:1152
	s_waitcnt lgkmcnt(0)
	s_barrier
	v_add_u32_e32 v169, s99, v168
	ds_read_b128 v[32:35], v169
	ds_read_b128 v[36:39], v169 offset:1024
	ds_read_b128 v[16:19], v169 offset:2048
	ds_read_b128 v[24:27], v169 offset:3072
	ds_read_b128 v[8:11], v169 offset:4096
	ds_read_b128 v[12:15], v169 offset:5120
	ds_read_b128 v[20:23], v169 offset:6144
	ds_read_b128 v[28:31], v169 offset:7168
	s_xor_b32 s99, s99, 0x4000
	ds_read2_b64 v[68:71], v144 offset1:4
	ds_read2_b64 v[60:63], v144 offset0:8 offset1:12
	s_waitcnt lgkmcnt(0)
	ds_write_b128 v93, v[40:43]
	s_waitcnt vmcnt(1)
	ds_write_b128 v93, v[48:51] offset:1152
	v_lshlrev_b32_e32 v40, 16, v112
	v_and_b32_e32 v41, 0xffff0000, v112
	v_lshlrev_b32_e32 v42, 16, v113
	v_and_b32_e32 v43, 0xffff0000, v113
	s_ashr_i32 s8, s0, 9
	s_and_b32 s14, s0, 0x1c0
	v_mfma_f32_16x16x32_bf16 v[32:35], v[32:35], v[0:3], v[40:43]
	s_add_i32 s13, s0, s10
	s_cmpk_lt_i32 s13, 0x1000
	s_cselect_b64 s[18:19], -1, 0
	v_mfma_f32_16x16x32_bf16 v[88:91], v[36:39], v[4:7], v[32:35]
	s_and_b64 vcc, s[18:19], exec
	s_cselect_b32 s18, s13, s0
	s_ashr_i32 s19, s18, 31
	s_nop 0
	v_lshlrev_b32_e32 v32, 16, v108
	v_and_b32_e32 v33, 0xffff0000, v108
	v_lshlrev_b32_e32 v34, 16, v109
	v_and_b32_e32 v35, 0xffff0000, v109
	v_add_f32_e32 v136, v88, v89
	v_add_f32_e32 v137, v90, v91
	v_mfma_f32_16x16x32_bf16 v[16:19], v[16:19], v[0:3], v[32:35]
	v_add_f32_e32 v136, v136, v137
	v_add_f32_e32 v136, 0, v136
	s_lshl_b64 s[0:1], s[18:19], 13
	v_mfma_f32_16x16x32_bf16 v[76:79], v[24:27], v[4:7], v[16:19]
	s_add_u32 s20, s3, s0
	s_addc_u32 s21, s16, s1
	s_waitcnt lgkmcnt(0)
	ds_read2_b64 v[72:75], v144 offset1:4
	ds_read2_b64 v[64:67], v144 offset0:8 offset1:12
	v_lshlrev_b32_e32 v16, 16, v114
	v_and_b32_e32 v17, 0xffff0000, v114
	v_lshlrev_b32_e32 v18, 16, v115
	v_and_b32_e32 v19, 0xffff0000, v115
	v_add_f32_e32 v137, v76, v77
	v_add_f32_e32 v138, v78, v79
	v_mfma_f32_16x16x32_bf16 v[8:11], v[8:11], v[0:3], v[16:19]
	v_add_f32_e32 v137, v137, v138
	v_add_f32_e32 v136, v136, v137
	s_waitcnt lgkmcnt(0)
	v_mfma_f32_16x16x32_bf16 v[80:83], v[12:15], v[4:7], v[8:11]
	v_lshl_add_u64 v[12:13], v[98:99], 1, s[20:21]
	s_waitcnt vmcnt(0)
	v_mov_b32_e32 v44, v57
	v_mov_b32_e32 v45, v58
	s_nop 0
	v_lshlrev_b32_e32 v8, 16, v110
	v_and_b32_e32 v9, 0xffff0000, v110
	v_lshlrev_b32_e32 v10, 16, v111
	v_and_b32_e32 v11, 0xffff0000, v111
	v_add_f32_e32 v137, v80, v81
	v_add_f32_e32 v138, v82, v83
	v_mfma_f32_16x16x32_bf16 v[0:3], v[20:23], v[0:3], v[8:11]
	v_add_f32_e32 v137, v137, v138
	v_add_f32_e32 v136, v136, v137
	v_lshl_add_u64 v[20:21], v[122:123], 0, s[0:1]
	v_mfma_f32_16x16x32_bf16 v[84:87], v[28:31], v[4:7], v[0:3]
	v_lshl_add_u64 v[4:5], v[124:125], 0, s[0:1]
	v_add_co_u32_e64 v40, s[0:1], s2, v20
	v_lshl_add_u64 v[8:9], v[94:95], 1, s[20:21]
	v_lshl_add_u64 v[164:165], v[170:171], 1, s[20:21]
	v_lshl_add_u64 v[178:179], v[172:173], 1, s[20:21]
	s_nop 0
	v_addc_co_u32_e64 v41, s[0:1], 0, v21, s[0:1]
	s_nop 2
	v_add_f32_e32 v137, v84, v85
	v_add_f32_e32 v138, v86, v87
	v_add_f32_e32 v137, v137, v138
	v_add_f32_e32 v136, v136, v137
	v_mov_b32_e32 v137, v136
	s_nop 1
	v_permlane32_swap_b32_e32 v136, v137
	v_add_f32_e32 v136, v136, v137
	v_mov_b32_e32 v137, v136
	s_nop 1
	v_permlane16_swap_b32_e32 v136, v137
	v_add_f32_e32 v136, v136, v137
	v_fmamk_f32 v151, v136, 0xbc800000, v91
	v_fmac_f32_e32 v89, 0xbc800000, v136
	v_fmamk_f32 v150, v136, 0xbc800000, v90
	v_fmamk_f32 v88, v136, 0xbc800000, v88
	v_mul_f32_e32 v90, v89, v89
	v_mul_f32_e32 v91, v151, v151
	v_fmac_f32_e32 v90, v88, v88
	v_fmac_f32_e32 v91, v150, v150
	s_ashr_i32 s0, s18, 6
	v_add_f32_e32 v137, v90, v91
	v_fmamk_f32 v91, v136, 0xbc800000, v79
	v_fmac_f32_e32 v77, 0xbc800000, v136
	s_ashr_i32 s1, s0, 31
	v_fmamk_f32 v90, v136, 0xbc800000, v78
	v_fmamk_f32 v76, v136, 0xbc800000, v76
	v_mul_f32_e32 v78, v77, v77
	v_mul_f32_e32 v79, v91, v91
	global_load_dwordx4 v[0:3], v[4:5], off nt
	s_nop 0
	global_load_dwordx4 v[4:7], v[4:5], off offset:1024 nt
	s_nop 0
	global_load_dwordx4 v[160:163], v[164:165], off nt
	global_load_dwordx4 v[174:177], v[178:179], off nt
	global_load_dwordx2 v[112:113], v[20:21], off nt
	s_nop 0
	s_nop 0
	global_load_dwordx2 v[108:109], v[20:21], off offset:2048 nt
	v_lshl_add_u64 v[8:9], v[96:97], 1, s[20:21]
	v_lshl_add_u64 v[20:21], v[100:101], 1, s[20:21]
	v_lshl_add_u64 v[28:29], v[102:103], 1, s[20:21]
	s_lshl_b64 s[20:21], s[0:1], 12
	s_lshl_b32 s1, s18, 6
	s_ashr_i32 s18, s18, 9
	v_fmac_f32_e32 v78, v76, v76
	v_fmac_f32_e32 v79, v90, v90
	s_ashr_i32 s19, s18, 31
	v_add_f32_e32 v78, v78, v79
	v_fmamk_f32 v83, v136, 0xbc800000, v83
	v_fmac_f32_e32 v81, 0xbc800000, v136
	v_mov_b32_e32 v57, v59
	s_lshl_b64 s[18:19], s[18:19], 12
	v_add_f32_e32 v78, v137, v78
	v_fmamk_f32 v82, v136, 0xbc800000, v82
	v_fmamk_f32 v80, v136, 0xbc800000, v80
	v_mul_f32_e32 v79, v81, v81
	v_mul_f32_e32 v137, v83, v83
	v_pk_add_f32 v[134:135], v[44:45], v[56:57]
	s_and_b32 s1, s1, 0xfc0
	v_or_b32_e32 v56, s18, v92
	v_fmac_f32_e32 v79, v80, v80
	v_fmac_f32_e32 v137, v82, v82
	v_or_b32_e32 v56, s1, v56
	v_add_f32_e32 v79, v79, v137
	v_mov_b32_e32 v57, s19
	v_or_b32_e32 v56, s6, v56
	v_add_f32_e32 v137, v79, v78
	v_fmamk_f32 v79, v136, 0xbc800000, v87
	v_fmac_f32_e32 v85, 0xbc800000, v136
	v_lshlrev_b64 v[56:57], 7, v[56:57]
	s_lshl_b32 s0, s0, 4
	v_fmamk_f32 v78, v136, 0xbc800000, v86
	v_fmamk_f32 v84, v136, 0xbc800000, v84
	v_mul_f32_e32 v86, v85, v85
	v_mul_f32_e32 v87, v79, v79
; __device__ __forceinline__ unsigned pk2(float lo, float hi) { f32x2_t v = {lo, hi}; bf16x2_t b = __builtin_convertvector(v, bf16x2_t); return __builtin_bit_cast(unsigned, b); }
; #define LDS_WAIT() asm volatile("s_waitcnt lgkmcnt(0)" ::: "memory")
; __device__ __forceinline__ f32x4 bf4(u32x2 w) { return (f32x4){__uint_as_float(w.x << 16), __uint_as_float(w.x & 0xffff0000u), __uint_as_float(w.y << 16), __uint_as_float(w.y & 0xffff0000u)}; }
; __device__ __forceinline__ void chunk_out(const PBArgs& A, unsigned char* lds, int G_, int wave, int lane) {
;     ...
;         { const int itn = (it + 2 * G_ < 4096) ? it + 2 * G_ : it; CO_LOAD(itn); }
;         float sm = 0.f;
; #pragma unroll
;         for (int vi = 0; vi < 4; ++vi) sm += (c[vi][0] + c[vi][1]) + (c[vi][2] + c[vi][3]);
;         sm = rows4_sum(sm);
;         const float mu = sm * (1.0f / 64.0f);
;         float q = 0.f;
; #pragma unroll
;         for (int vi = 0; vi < 4; ++vi) { c[vi] = c[vi] - mu; q += (c[vi][0] * c[vi][0] + c[vi][1] * c[vi][1]) + (c[vi][2] * c[vi][2] + c[vi][3] * c[vi][3]); }
;         q = rows4_sum(q);
;         const float rs = rsqrtf(q * (1.0f / 64.0f) + 64e-5f);
; #pragma unroll
;         for (int vi = 0; vi < 4; ++vi) {
;             const f32x4 lg = *(const f32x4*)(A.lnx_g + h * 64 + vi * 16 + fq * 4), lb = *(const f32x4*)(A.lnx_b + h * 64 + vi * 16 + fq * 4);
;             const f32x4 o = (c[vi] * rs * lg + lb + bf4(vv[vi]) * rk) * bf4(gg[vi]);
;             *(u32x2*)(ostg + fr * 144 + (vi * 16 + fq * 4) * 2) = (u32x2){pk2(o[0], o[1]), pk2(o[2], o[3])};
;         }
;         LDS_WAIT();
; #pragma unroll
;         for (int j = 0; j < 2; ++j) {
;             const int tk = (lane >> 3) + 8 * j, c16 = lane & 7;
;             const size_t tg = (size_t)b * SEQ + ck * 64 + tt * 16 + tk;
;             *(u32x4*)(YA + tg * 512 + h * 64 + c16 * 8) = *(const u32x4*)(ostg + tk * 144 + c16 * 16);
;         }
;         LDS_WAIT();
	v_lshl_add_u64 v[56:57], s[22:23], 0, v[56:57]
	s_and_b32 s4, s0, 0x70
	v_fmac_f32_e32 v86, v84, v84
	v_fmac_f32_e32 v87, v78, v78
	v_lshl_add_u64 v[56:57], v[56:57], 0, s[4:5]
	v_add_f32_e32 v86, v86, v87
	s_lshl_b32 s4, s14, 2
	v_add_f32_e32 v86, v86, v137
	v_add_u32_e32 v136, s4, v159
	s_nop 0
	s_nop 0
	v_mov_b32_e32 v87, v86
	s_nop 0
	s_nop 0
	v_permlane32_swap_b32_e32 v86, v87
	global_load_dwordx2 v[114:115], v[40:41], off nt
	v_add_f32_e32 v86, v86, v87
	s_nop 0
	s_nop 0
	s_nop 0
	s_nop 0
	global_load_dwordx2 v[110:111], v[40:41], off offset:2048 nt
	ds_read_b128 v[140:143], v136
	ds_read_b128 v[146:149], v136 offset:2048
	v_mov_b32_e32 v87, v86
	s_nop 1
	v_permlane16_swap_b32_e32 v86, v87
	v_add_f32_e32 v86, v86, v87
	v_fmamk_f32 v86, v86, 0x3c800000, v145
	s_mov_b32 s0, 0x800000
	s_or_b32 s20, s20, s1
	v_cmp_gt_f32_e64 s[0:1], s0, v86
	v_mul_f32_e32 v87, 0x4b800000, v86
	s_or_b64 s[20:21], s[20:21], s[6:7]
	v_cndmask_b32_e64 v86, v86, v87, s[0:1]
	v_rsq_f32_e32 v86, v86
	s_lshl_b64 s[20:21], s[20:21], 7
	v_lshl_add_u64 v[48:49], v[116:117], 0, s[20:21]
	v_lshl_add_u64 v[50:51], v[118:119], 0, s[20:21]
	v_mul_f32_e32 v87, 0x45800000, v86
	v_cndmask_b32_e64 v86, v86, v87, s[0:1]
	v_pk_mul_f32 v[152:153], v[88:89], v[86:87] op_sel_hi:[1,0]
	v_pk_mul_f32 v[88:89], v[150:151], v[86:87] op_sel_hi:[1,0]
	v_lshl_add_u64 v[40:41], v[48:49], 0, v[130:131]
	v_lshl_add_u64 v[48:49], v[48:49], 0, v[132:133]
	v_add_f32_e32 v134, v134, v135
	global_load_dwordx4 v[44:47], v[40:41], off nt
	global_load_dwordx4 v[52:55], v[48:49], off nt
	v_lshl_add_u64 v[40:41], v[50:51], 0, v[130:131]
	v_lshl_add_u64 v[48:49], v[50:51], 0, v[132:133]
	global_load_dwordx4 v[40:43], v[40:41], off nt
	s_ashr_i32 s9, s8, 31
	global_load_dwordx4 v[48:51], v[48:49], off nt
	s_and_b32 s4, s11, 0xfc0
	global_load_dwordx4 v[56:59], v[56:57], off nt
	s_lshl_b64 s[0:1], s[8:9], 12
	s_or_b32 s4, s4, s6
	s_or_b32 s0, s0, s4
	s_lshl_b32 s4, s14, 1
	s_add_i32 s11, s11, s12
	s_nop 0
	s_waitcnt lgkmcnt(0)
	v_pk_fma_f32 v[88:89], v[142:143], v[88:89], v[148:149]
	v_pk_fma_f32 v[140:141], v[140:141], v[152:153], v[146:147]
	s_nop 0
	v_lshlrev_b32_e32 v142, 16, v68
	v_and_b32_e32 v143, 0xffff0000, v68
	v_lshlrev_b32_e32 v68, 16, v69
	v_and_b32_e32 v69, 0xffff0000, v69
	v_pk_fma_f32 v[140:141], v[134:135], v[142:143], v[140:141] op_sel_hi:[0,1,1]
	v_pk_fma_f32 v[68:69], v[134:135], v[68:69], v[88:89] op_sel_hi:[0,1,1]
	s_nop 0
	v_lshlrev_b32_e32 v88, 16, v72
	v_and_b32_e32 v89, 0xffff0000, v72
	v_lshlrev_b32_e32 v72, 16, v73
	v_and_b32_e32 v73, 0xffff0000, v73
	v_pk_mul_f32 v[68:69], v[68:69], v[72:73]
	v_pk_mul_f32 v[72:73], v[140:141], v[88:89]
	ds_read_b128 v[140:143], v136 offset:64
	ds_read_b128 v[146:149], v136 offset:2112
	v_cvt_pk_bf16_f32 v72, v72, v73
	v_cvt_pk_bf16_f32 v73, v68, v69
	v_pk_mul_f32 v[68:69], v[76:77], v[86:87] op_sel_hi:[1,0]
	v_pk_mul_f32 v[76:77], v[90:91], v[86:87] op_sel_hi:[1,0]
	v_lshlrev_b32_e32 v88, 16, v70
	v_and_b32_e32 v89, 0xffff0000, v70
	v_lshlrev_b32_e32 v70, 16, v71
	v_and_b32_e32 v71, 0xffff0000, v71
	s_nop 0
	s_waitcnt lgkmcnt(0)
	v_pk_fma_f32 v[76:77], v[142:143], v[76:77], v[148:149]
	v_pk_fma_f32 v[68:69], v[140:141], v[68:69], v[146:147]
	v_pk_fma_f32 v[70:71], v[134:135], v[70:71], v[76:77] op_sel_hi:[0,1,1]
	v_pk_fma_f32 v[68:69], v[134:135], v[88:89], v[68:69] op_sel_hi:[0,1,1]
	v_lshlrev_b32_e32 v76, 16, v74
	v_and_b32_e32 v77, 0xffff0000, v74
	v_lshlrev_b32_e32 v74, 16, v75
	v_and_b32_e32 v75, 0xffff0000, v75
	v_pk_mul_f32 v[70:71], v[70:71], v[74:75]
	v_pk_mul_f32 v[68:69], v[68:69], v[76:77]
	v_pk_mul_f32 v[76:77], v[80:81], v[86:87] op_sel_hi:[1,0]
	v_cvt_pk_bf16_f32 v68, v68, v69
	v_cvt_pk_bf16_f32 v69, v70, v71
	ds_write2_b64 v144, v[72:73], v[68:69] offset1:4
	ds_read_b128 v[68:71], v136 offset:128
	ds_read_b128 v[72:75], v136 offset:2176
	v_pk_mul_f32 v[80:81], v[82:83], v[86:87] op_sel_hi:[1,0]
	s_nop 0
	s_waitcnt lgkmcnt(0)
	v_pk_fma_f32 v[68:69], v[68:69], v[76:77], v[72:73]
	v_pk_fma_f32 v[70:71], v[70:71], v[80:81], v[74:75]
	v_lshlrev_b32_e32 v72, 16, v60
	v_and_b32_e32 v73, 0xffff0000, v60
	v_lshlrev_b32_e32 v60, 16, v61
	v_and_b32_e32 v61, 0xffff0000, v61
	v_pk_fma_f32 v[68:69], v[134:135], v[72:73], v[68:69] op_sel_hi:[0,1,1]
	v_pk_fma_f32 v[60:61], v[134:135], v[60:61], v[70:71] op_sel_hi:[0,1,1]
	s_nop 0
	v_lshlrev_b32_e32 v70, 16, v64
	v_and_b32_e32 v71, 0xffff0000, v64
	v_lshlrev_b32_e32 v64, 16, v65
	v_and_b32_e32 v65, 0xffff0000, v65
	v_pk_mul_f32 v[60:61], v[60:61], v[64:65]
	v_pk_mul_f32 v[64:65], v[68:69], v[70:71]
	ds_read_b128 v[68:71], v136 offset:192
	ds_read_b128 v[72:75], v136 offset:2240
	v_cvt_pk_bf16_f32 v64, v64, v65
	v_cvt_pk_bf16_f32 v65, v60, v61
	v_pk_mul_f32 v[60:61], v[84:85], v[86:87] op_sel_hi:[1,0]
	v_pk_mul_f32 v[76:77], v[78:79], v[86:87] op_sel_hi:[1,0]
	s_nop 0
	s_waitcnt lgkmcnt(0)
	v_pk_fma_f32 v[60:61], v[68:69], v[60:61], v[72:73]
	v_pk_fma_f32 v[70:71], v[70:71], v[76:77], v[74:75]
	v_lshlrev_b32_e32 v68, 16, v62
	v_and_b32_e32 v69, 0xffff0000, v62
	v_lshlrev_b32_e32 v62, 16, v63
	v_and_b32_e32 v63, 0xffff0000, v63
	v_pk_fma_f32 v[60:61], v[134:135], v[68:69], v[60:61] op_sel_hi:[0,1,1]
	v_pk_fma_f32 v[62:63], v[134:135], v[62:63], v[70:71] op_sel_hi:[0,1,1]
	v_lshlrev_b32_e32 v68, 16, v66
	v_and_b32_e32 v69, 0xffff0000, v66
	v_lshlrev_b32_e32 v66, 16, v67
	v_and_b32_e32 v67, 0xffff0000, v67
	v_pk_mul_f32 v[62:63], v[62:63], v[66:67]
	v_pk_mul_f32 v[60:61], v[60:61], v[68:69]
	v_lshl_add_u64 v[66:67], s[0:1], 0, v[104:105]
	v_cvt_pk_bf16_f32 v60, v60, v61
	v_cvt_pk_bf16_f32 v61, v62, v63
	ds_write2_b64 v144, v[64:65], v[60:61] offset0:8 offset1:12
	s_waitcnt lgkmcnt(0)
	ds_read_b128 v[60:63], v93
	v_lshl_add_u64 v[64:65], v[120:121], 0, s[4:5]
	v_lshlrev_b64 v[66:67], 10, v[66:67]
	v_lshl_add_u64 v[66:67], v[64:65], 0, v[66:67]
	s_nop 0
	s_waitcnt lgkmcnt(0)
	global_store_dwordx4 v[66:67], v[60:63], off
	ds_read_b128 v[60:63], v93 offset:1152
	v_lshl_add_u64 v[66:67], s[0:1], 0, v[106:107]
	v_lshlrev_b64 v[66:67], 10, v[66:67]
	v_lshl_add_u64 v[64:65], v[64:65], 0, v[66:67]
	s_mov_b32 s0, s13
	s_nop 0
	s_waitcnt lgkmcnt(0)
	global_store_dwordx4 v[64:65], v[60:63], off
	s_waitcnt lgkmcnt(0)
	s_cbranch_vccnz .LBB0_577

; __device__ __forceinline__ unsigned cvt_pk_bf16(float lo, float hi) { unsigned r; asm volatile("v_cvt_pk_bf16_f32 %0, %1, %2" : "=v"(r) : "v"(lo), "v"(hi)); return r; }
;     __device__ __forceinline__ void operator()(const f32x4 (&acc)[2][2][4][2], const Unit& u, int wr, int wc, int fr, int fq) const {
;     ...
;         for (int ai = 0; ai < 2; ++ai)
; #pragma unroll
;             for (int m = 0; m < 4; ++m) {
;                 const size_t row = (size_t)(row0 + ai * HALF + m * 16);
; #pragma unroll
;                 for (int bj = 0; bj < 2; ++bj) {
;                     const int col = col0 + bj * HALF;
;                     f32x4 g0, g1; bf8(*(const u32x4*)(Q + row * QW + (MODE == 0 ? QC_GA : QC_GB) + col), g0, g1);
;                     f32x4 v0 = acc[ai][bj][m][0] * g0, v1 = acc[ai][bj][m][1] * g1;
;                     if (MODE == 1) { f32x4 t0, t1; bf8(*(const u32x4*)(merged + row * D + col), t0, t1); v0 += t0; v1 += t1; }
;                     u32x4 w; w.x = cvt_pk_bf16(v0[0], v0[1]); w.y = cvt_pk_bf16(v0[2], v0[3]); w.z = cvt_pk_bf16(v1[0], v1[1]); w.w = cvt_pk_bf16(v1[2], v1[3]);
;                     *(u32x4*)(merged + row * D + col) = w;
;                 }
.LBB0_646:
	v_lshl_add_u32 v144, s45, 8, v152
	v_lshl_add_u32 v146, s18, 8, v150
	v_mov_b64_e32 v[148:149], s[60:61]
	v_ashrrev_i32_e32 v145, 31, v144
	v_mad_i64_i32 v[156:157], s[20:21], v146, s44, v[148:149]
	v_lshlrev_b64 v[144:145], 1, v[144:145]
	v_lshl_add_u64 v[160:161], v[156:157], 0, v[144:145]
	global_load_dwordx4 v[156:159], v[160:161], off offset:1536 nt
	v_ashrrev_i32_e32 v147, 31, v146
	v_readlane_b32 s22, v241, 19
	v_readlane_b32 s23, v241, 20
	s_andn2_b64 vcc, exec, s[0:1]
	s_mov_b64 s[0:1], -1
	s_waitcnt vmcnt(0)
	v_lshlrev_b32_e32 v162, 16, v156
	v_and_b32_e32 v163, 0xffff0000, v156
	v_lshlrev_b32_e32 v156, 16, v157
	v_and_b32_e32 v157, 0xffff0000, v157
	v_lshlrev_b32_e32 v164, 16, v158
	v_and_b32_e32 v165, 0xffff0000, v158
	v_lshlrev_b32_e32 v158, 16, v159
	v_and_b32_e32 v159, 0xffff0000, v159
	v_pk_mul_f32 v[126:127], v[126:127], v[156:157]
	v_pk_mul_f32 v[124:125], v[124:125], v[162:163]
	v_pk_mul_f32 v[156:157], v[122:123], v[158:159]
	v_pk_mul_f32 v[122:123], v[120:121], v[164:165]
	v_cvt_pk_bf16_f32 v120, v124, v125
	v_cvt_pk_bf16_f32 v121, v126, v127
	v_lshlrev_b64 v[158:159], 11, v[146:147]
	v_cvt_pk_bf16_f32 v122, v122, v123
	v_cvt_pk_bf16_f32 v123, v156, v157
	global_load_dwordx4 v[124:127], v[160:161], off offset:1792 nt
	v_lshl_add_u64 v[158:159], s[22:23], 0, v[158:159]
	v_or_b32_e32 v156, 16, v146
	v_lshl_add_u64 v[158:159], v[158:159], 0, v[144:145]
	v_mad_i64_i32 v[160:161], s[20:21], v156, s44, v[148:149]
	global_store_dwordx4 v[158:159], v[120:123], off
	v_lshl_add_u64 v[160:161], v[160:161], 0, v[144:145]
	v_ashrrev_i32_e32 v157, 31, v156
	s_waitcnt vmcnt(1)
	v_lshlrev_b32_e32 v120, 16, v124
	v_and_b32_e32 v121, 0xffff0000, v124
	v_lshlrev_b32_e32 v122, 16, v125
	v_and_b32_e32 v123, 0xffff0000, v125
	v_lshlrev_b32_e32 v124, 16, v126
	v_and_b32_e32 v125, 0xffff0000, v126
	v_lshlrev_b32_e32 v126, 16, v127
	v_and_b32_e32 v127, 0xffff0000, v127
	v_pk_mul_f32 v[114:115], v[114:115], v[122:123]
	v_pk_mul_f32 v[112:113], v[112:113], v[120:121]
	v_pk_mul_f32 v[120:121], v[110:111], v[126:127]
	v_pk_mul_f32 v[110:111], v[108:109], v[124:125]
	v_cvt_pk_bf16_f32 v108, v112, v113
	v_cvt_pk_bf16_f32 v109, v114, v115
	s_nop 0
	v_cvt_pk_bf16_f32 v110, v110, v111
	v_cvt_pk_bf16_f32 v111, v120, v121
	global_load_dwordx4 v[112:115], v[160:161], off offset:1536 nt
	s_nop 0
	global_store_dwordx4 v[158:159], v[108:111], off offset:256
	s_waitcnt vmcnt(1)
	s_nop 0
	v_lshlrev_b32_e32 v108, 16, v112
	v_and_b32_e32 v109, 0xffff0000, v112
	v_lshlrev_b32_e32 v110, 16, v113
	v_and_b32_e32 v111, 0xffff0000, v113
	v_lshlrev_b32_e32 v112, 16, v114
	v_and_b32_e32 v113, 0xffff0000, v114
	v_lshlrev_b32_e32 v114, 16, v115
	v_and_b32_e32 v115, 0xffff0000, v115
	v_pk_mul_f32 v[110:111], v[118:119], v[110:111]
	v_pk_mul_f32 v[108:109], v[116:117], v[108:109]
	v_pk_mul_f32 v[114:115], v[106:107], v[114:115]
	v_pk_mul_f32 v[106:107], v[104:105], v[112:113]
	v_cvt_pk_bf16_f32 v104, v108, v109
	v_cvt_pk_bf16_f32 v105, v110, v111
	v_lshlrev_b64 v[116:117], 11, v[156:157]
	v_cvt_pk_bf16_f32 v106, v106, v107
	v_cvt_pk_bf16_f32 v107, v114, v115
	global_load_dwordx4 v[108:111], v[160:161], off offset:1792 nt
	v_lshl_add_u64 v[116:117], s[22:23], 0, v[116:117]
	v_or_b32_e32 v112, 32, v146
	v_lshl_add_u64 v[116:117], v[116:117], 0, v[144:145]
	v_mad_i64_i32 v[114:115], s[20:21], v112, s44, v[148:149]
	global_store_dwordx4 v[116:117], v[104:107], off
	v_lshl_add_u64 v[114:115], v[114:115], 0, v[144:145]
	v_ashrrev_i32_e32 v113, 31, v112
	s_waitcnt vmcnt(1)
	v_lshlrev_b32_e32 v104, 16, v108
	v_and_b32_e32 v105, 0xffff0000, v108
	v_lshlrev_b32_e32 v106, 16, v109
	v_and_b32_e32 v107, 0xffff0000, v109
	v_lshlrev_b32_e32 v108, 16, v110
	v_and_b32_e32 v109, 0xffff0000, v110
	v_lshlrev_b32_e32 v110, 16, v111
	v_and_b32_e32 v111, 0xffff0000, v111
	v_pk_mul_f32 v[98:99], v[98:99], v[106:107]
	v_pk_mul_f32 v[96:97], v[96:97], v[104:105]
	v_pk_mul_f32 v[104:105], v[94:95], v[110:111]
	v_pk_mul_f32 v[94:95], v[92:93], v[108:109]
	v_cvt_pk_bf16_f32 v92, v96, v97
	v_cvt_pk_bf16_f32 v93, v98, v99
	s_nop 0
	v_cvt_pk_bf16_f32 v94, v94, v95
	v_cvt_pk_bf16_f32 v95, v104, v105
	global_load_dwordx4 v[96:99], v[114:115], off offset:1536 nt
	s_nop 0
	global_store_dwordx4 v[116:117], v[92:95], off offset:256
	s_waitcnt vmcnt(1)
	s_nop 0
	v_lshlrev_b32_e32 v92, 16, v96
	v_and_b32_e32 v93, 0xffff0000, v96
	v_lshlrev_b32_e32 v94, 16, v97
	v_and_b32_e32 v95, 0xffff0000, v97
	v_lshlrev_b32_e32 v96, 16, v98
	v_and_b32_e32 v97, 0xffff0000, v98
	v_lshlrev_b32_e32 v98, 16, v99
	v_and_b32_e32 v99, 0xffff0000, v99
	v_pk_mul_f32 v[94:95], v[102:103], v[94:95]
	v_pk_mul_f32 v[92:93], v[100:101], v[92:93]
	v_pk_mul_f32 v[98:99], v[90:91], v[98:99]
	v_pk_mul_f32 v[90:91], v[88:89], v[96:97]
	v_cvt_pk_bf16_f32 v88, v92, v93
	v_cvt_pk_bf16_f32 v89, v94, v95
	v_lshlrev_b64 v[100:101], 11, v[112:113]
	v_cvt_pk_bf16_f32 v90, v90, v91
	v_cvt_pk_bf16_f32 v91, v98, v99
	global_load_dwordx4 v[92:95], v[114:115], off offset:1792 nt
	v_lshl_add_u64 v[100:101], s[22:23], 0, v[100:101]
	v_or_b32_e32 v96, 48, v146
	v_lshl_add_u64 v[100:101], v[100:101], 0, v[144:145]
	v_mad_i64_i32 v[98:99], s[20:21], v96, s44, v[148:149]
	global_store_dwordx4 v[100:101], v[88:91], off
	v_lshl_add_u64 v[98:99], v[98:99], 0, v[144:145]
	v_ashrrev_i32_e32 v97, 31, v96
	s_waitcnt vmcnt(1)
; __device__ __forceinline__ unsigned cvt_pk_bf16(float lo, float hi) { unsigned r; asm volatile("v_cvt_pk_bf16_f32 %0, %1, %2" : "=v"(r) : "v"(lo), "v"(hi)); return r; }
;     __device__ __forceinline__ void operator()(const f32x4 (&acc)[2][2][4][2], const Unit& u, int wr, int wc, int fr, int fq) const {
;     ...
;         for (int ai = 0; ai < 2; ++ai)
; #pragma unroll
;             for (int m = 0; m < 4; ++m) {
;                 const size_t row = (size_t)(row0 + ai * HALF + m * 16);
; #pragma unroll
;                 for (int bj = 0; bj < 2; ++bj) {
;                     const int col = col0 + bj * HALF;
;                     f32x4 g0, g1; bf8(*(const u32x4*)(Q + row * QW + (MODE == 0 ? QC_GA : QC_GB) + col), g0, g1);
;                     f32x4 v0 = acc[ai][bj][m][0] * g0, v1 = acc[ai][bj][m][1] * g1;
;                     if (MODE == 1) { f32x4 t0, t1; bf8(*(const u32x4*)(merged + row * D + col), t0, t1); v0 += t0; v1 += t1; }
;                     u32x4 w; w.x = cvt_pk_bf16(v0[0], v0[1]); w.y = cvt_pk_bf16(v0[2], v0[3]); w.z = cvt_pk_bf16(v1[0], v1[1]); w.w = cvt_pk_bf16(v1[2], v1[3]);
;                     *(u32x4*)(merged + row * D + col) = w;
;                 }
	v_lshlrev_b32_e32 v88, 16, v92
	v_and_b32_e32 v89, 0xffff0000, v92
	v_lshlrev_b32_e32 v90, 16, v93
	v_and_b32_e32 v91, 0xffff0000, v93
	v_lshlrev_b32_e32 v92, 16, v94
	v_and_b32_e32 v93, 0xffff0000, v94
	v_lshlrev_b32_e32 v94, 16, v95
	v_and_b32_e32 v95, 0xffff0000, v95
	v_pk_mul_f32 v[82:83], v[82:83], v[90:91]
	v_pk_mul_f32 v[80:81], v[80:81], v[88:89]
	v_pk_mul_f32 v[88:89], v[78:79], v[94:95]
	v_pk_mul_f32 v[78:79], v[76:77], v[92:93]
	v_cvt_pk_bf16_f32 v76, v80, v81
	v_cvt_pk_bf16_f32 v77, v82, v83
	s_nop 0
	v_cvt_pk_bf16_f32 v78, v78, v79
	v_cvt_pk_bf16_f32 v79, v88, v89
	global_load_dwordx4 v[80:83], v[98:99], off offset:1536 nt
	s_nop 0
	global_store_dwordx4 v[100:101], v[76:79], off offset:256
	s_waitcnt vmcnt(1)
	s_nop 0
	v_lshlrev_b32_e32 v76, 16, v80
	v_and_b32_e32 v77, 0xffff0000, v80
	v_lshlrev_b32_e32 v78, 16, v81
	v_and_b32_e32 v79, 0xffff0000, v81
	v_lshlrev_b32_e32 v80, 16, v82
	v_and_b32_e32 v81, 0xffff0000, v82
	v_lshlrev_b32_e32 v82, 16, v83
	v_and_b32_e32 v83, 0xffff0000, v83
	v_pk_mul_f32 v[78:79], v[86:87], v[78:79]
	v_pk_mul_f32 v[76:77], v[84:85], v[76:77]
	v_pk_mul_f32 v[82:83], v[74:75], v[82:83]
	v_pk_mul_f32 v[74:75], v[72:73], v[80:81]
	v_cvt_pk_bf16_f32 v72, v76, v77
	v_cvt_pk_bf16_f32 v73, v78, v79
	v_lshlrev_b64 v[84:85], 11, v[96:97]
	v_cvt_pk_bf16_f32 v74, v74, v75
	v_cvt_pk_bf16_f32 v75, v82, v83
	global_load_dwordx4 v[76:79], v[98:99], off offset:1792 nt
	v_lshl_add_u64 v[84:85], s[22:23], 0, v[84:85]
	v_add_u32_e32 v80, 0x80, v146
	v_lshl_add_u64 v[84:85], v[84:85], 0, v[144:145]
	v_mad_i64_i32 v[82:83], s[20:21], v80, s44, v[148:149]
	global_store_dwordx4 v[84:85], v[72:75], off
	v_lshl_add_u64 v[82:83], v[82:83], 0, v[144:145]
	v_ashrrev_i32_e32 v81, 31, v80
	s_waitcnt vmcnt(1)
	v_lshlrev_b32_e32 v72, 16, v76
	v_and_b32_e32 v73, 0xffff0000, v76
	v_lshlrev_b32_e32 v74, 16, v77
	v_and_b32_e32 v75, 0xffff0000, v77
	v_lshlrev_b32_e32 v76, 16, v78
	v_and_b32_e32 v77, 0xffff0000, v78
	v_lshlrev_b32_e32 v78, 16, v79
	v_and_b32_e32 v79, 0xffff0000, v79
	v_pk_mul_f32 v[70:71], v[70:71], v[74:75]
	v_pk_mul_f32 v[68:69], v[68:69], v[72:73]
	v_pk_mul_f32 v[72:73], v[66:67], v[78:79]
	v_pk_mul_f32 v[66:67], v[64:65], v[76:77]
	v_cvt_pk_bf16_f32 v64, v68, v69
	v_cvt_pk_bf16_f32 v65, v70, v71
	s_nop 0
	v_cvt_pk_bf16_f32 v66, v66, v67
	v_cvt_pk_bf16_f32 v67, v72, v73
	global_load_dwordx4 v[68:71], v[82:83], off offset:1536 nt
	s_nop 0
	global_store_dwordx4 v[84:85], v[64:67], off offset:256
	s_waitcnt vmcnt(1)
	s_nop 0
	v_lshlrev_b32_e32 v64, 16, v68
	v_and_b32_e32 v65, 0xffff0000, v68
	v_lshlrev_b32_e32 v66, 16, v69
	v_and_b32_e32 v67, 0xffff0000, v69
	v_lshlrev_b32_e32 v68, 16, v70
	v_and_b32_e32 v69, 0xffff0000, v70
	v_lshlrev_b32_e32 v70, 16, v71
	v_and_b32_e32 v71, 0xffff0000, v71
	v_pk_mul_f32 v[62:63], v[62:63], v[66:67]
	v_pk_mul_f32 v[60:61], v[60:61], v[64:65]
	v_pk_mul_f32 v[64:65], v[58:59], v[70:71]
	v_pk_mul_f32 v[58:59], v[56:57], v[68:69]
	v_cvt_pk_bf16_f32 v56, v60, v61
	v_cvt_pk_bf16_f32 v57, v62, v63
	v_lshlrev_b64 v[68:69], 11, v[80:81]
	v_cvt_pk_bf16_f32 v58, v58, v59
	v_cvt_pk_bf16_f32 v59, v64, v65
	global_load_dwordx4 v[60:63], v[82:83], off offset:1792 nt
	v_lshl_add_u64 v[68:69], s[22:23], 0, v[68:69]
	v_add_u32_e32 v64, 0x90, v146
	v_lshl_add_u64 v[68:69], v[68:69], 0, v[144:145]
	v_mad_i64_i32 v[66:67], s[20:21], v64, s44, v[148:149]
	global_store_dwordx4 v[68:69], v[56:59], off
	v_lshl_add_u64 v[66:67], v[66:67], 0, v[144:145]
	v_ashrrev_i32_e32 v65, 31, v64
	s_waitcnt vmcnt(1)
	v_lshlrev_b32_e32 v56, 16, v60
	v_and_b32_e32 v57, 0xffff0000, v60
	v_lshlrev_b32_e32 v58, 16, v61
	v_and_b32_e32 v59, 0xffff0000, v61
	v_lshlrev_b32_e32 v60, 16, v62
	v_and_b32_e32 v61, 0xffff0000, v62
	v_lshlrev_b32_e32 v62, 16, v63
	v_and_b32_e32 v63, 0xffff0000, v63
	v_pk_mul_f32 v[50:51], v[50:51], v[58:59]
	v_pk_mul_f32 v[48:49], v[48:49], v[56:57]
	v_pk_mul_f32 v[56:57], v[46:47], v[62:63]
	v_pk_mul_f32 v[46:47], v[44:45], v[60:61]
	v_cvt_pk_bf16_f32 v44, v48, v49
	v_cvt_pk_bf16_f32 v45, v50, v51
	s_nop 0
	v_cvt_pk_bf16_f32 v46, v46, v47
	v_cvt_pk_bf16_f32 v47, v56, v57
	global_load_dwordx4 v[48:51], v[66:67], off offset:1536 nt
	s_nop 0
	global_store_dwordx4 v[68:69], v[44:47], off offset:256
	s_waitcnt vmcnt(1)
; __device__ __forceinline__ unsigned cvt_pk_bf16(float lo, float hi) { unsigned r; asm volatile("v_cvt_pk_bf16_f32 %0, %1, %2" : "=v"(r) : "v"(lo), "v"(hi)); return r; }
;     __device__ __forceinline__ void operator()(const f32x4 (&acc)[2][2][4][2], const Unit& u, int wr, int wc, int fr, int fq) const {
;     ...
;         for (int ai = 0; ai < 2; ++ai)
; #pragma unroll
;             for (int m = 0; m < 4; ++m) {
;                 const size_t row = (size_t)(row0 + ai * HALF + m * 16);
; #pragma unroll
;                 for (int bj = 0; bj < 2; ++bj) {
;                     const int col = col0 + bj * HALF;
;                     f32x4 g0, g1; bf8(*(const u32x4*)(Q + row * QW + (MODE == 0 ? QC_GA : QC_GB) + col), g0, g1);
;                     f32x4 v0 = acc[ai][bj][m][0] * g0, v1 = acc[ai][bj][m][1] * g1;
;                     if (MODE == 1) { f32x4 t0, t1; bf8(*(const u32x4*)(merged + row * D + col), t0, t1); v0 += t0; v1 += t1; }
;                     u32x4 w; w.x = cvt_pk_bf16(v0[0], v0[1]); w.y = cvt_pk_bf16(v0[2], v0[3]); w.z = cvt_pk_bf16(v1[0], v1[1]); w.w = cvt_pk_bf16(v1[2], v1[3]);
;                     *(u32x4*)(merged + row * D + col) = w;
;                 }
	s_nop 0
	v_lshlrev_b32_e32 v44, 16, v48
	v_and_b32_e32 v45, 0xffff0000, v48
	v_lshlrev_b32_e32 v46, 16, v49
	v_and_b32_e32 v47, 0xffff0000, v49
	v_lshlrev_b32_e32 v48, 16, v50
	v_and_b32_e32 v49, 0xffff0000, v50
	v_lshlrev_b32_e32 v50, 16, v51
	v_and_b32_e32 v51, 0xffff0000, v51
	v_pk_mul_f32 v[46:47], v[54:55], v[46:47]
	v_pk_mul_f32 v[44:45], v[52:53], v[44:45]
	v_pk_mul_f32 v[50:51], v[42:43], v[50:51]
	v_pk_mul_f32 v[42:43], v[40:41], v[48:49]
	v_cvt_pk_bf16_f32 v40, v44, v45
	v_cvt_pk_bf16_f32 v41, v46, v47
	v_lshlrev_b64 v[52:53], 11, v[64:65]
	v_cvt_pk_bf16_f32 v42, v42, v43
	v_cvt_pk_bf16_f32 v43, v50, v51
	global_load_dwordx4 v[44:47], v[66:67], off offset:1792 nt
	v_lshl_add_u64 v[52:53], s[22:23], 0, v[52:53]
	v_add_u32_e32 v48, 0xa0, v146
	v_lshl_add_u64 v[52:53], v[52:53], 0, v[144:145]
	v_mad_i64_i32 v[50:51], s[20:21], v48, s44, v[148:149]
	global_store_dwordx4 v[52:53], v[40:43], off
	v_lshl_add_u64 v[50:51], v[50:51], 0, v[144:145]
	v_ashrrev_i32_e32 v49, 31, v48
	s_waitcnt vmcnt(1)
	v_lshlrev_b32_e32 v40, 16, v44
	v_and_b32_e32 v41, 0xffff0000, v44
	v_lshlrev_b32_e32 v42, 16, v45
	v_and_b32_e32 v43, 0xffff0000, v45
	v_lshlrev_b32_e32 v44, 16, v46
	v_and_b32_e32 v45, 0xffff0000, v46
	v_lshlrev_b32_e32 v46, 16, v47
	v_and_b32_e32 v47, 0xffff0000, v47
	v_pk_mul_f32 v[34:35], v[34:35], v[42:43]
	v_pk_mul_f32 v[32:33], v[32:33], v[40:41]
	v_pk_mul_f32 v[40:41], v[30:31], v[46:47]
	v_pk_mul_f32 v[30:31], v[28:29], v[44:45]
	v_cvt_pk_bf16_f32 v28, v32, v33
	v_cvt_pk_bf16_f32 v29, v34, v35
	s_nop 0
	v_cvt_pk_bf16_f32 v30, v30, v31
	v_cvt_pk_bf16_f32 v31, v40, v41
	global_load_dwordx4 v[32:35], v[50:51], off offset:1536 nt
	s_nop 0
	global_store_dwordx4 v[52:53], v[28:31], off offset:256
	s_waitcnt vmcnt(1)
	s_nop 0
	v_lshlrev_b32_e32 v28, 16, v32
	v_and_b32_e32 v29, 0xffff0000, v32
	v_lshlrev_b32_e32 v30, 16, v33
	v_and_b32_e32 v31, 0xffff0000, v33
	v_lshlrev_b32_e32 v32, 16, v34
	v_and_b32_e32 v33, 0xffff0000, v34
	v_lshlrev_b32_e32 v34, 16, v35
	v_and_b32_e32 v35, 0xffff0000, v35
	v_pk_mul_f32 v[30:31], v[38:39], v[30:31]
	v_pk_mul_f32 v[28:29], v[36:37], v[28:29]
	v_pk_mul_f32 v[34:35], v[26:27], v[34:35]
	v_pk_mul_f32 v[26:27], v[24:25], v[32:33]
	v_cvt_pk_bf16_f32 v24, v28, v29
	v_cvt_pk_bf16_f32 v25, v30, v31
	v_lshlrev_b64 v[36:37], 11, v[48:49]
	v_cvt_pk_bf16_f32 v26, v26, v27
	v_cvt_pk_bf16_f32 v27, v34, v35
	global_load_dwordx4 v[28:31], v[50:51], off offset:1792 nt
	v_lshl_add_u64 v[36:37], s[22:23], 0, v[36:37]
	v_add_u32_e32 v32, 0xb0, v146
	v_lshl_add_u64 v[36:37], v[36:37], 0, v[144:145]
	v_mad_i64_i32 v[34:35], s[20:21], v32, s44, v[148:149]
	global_store_dwordx4 v[36:37], v[24:27], off
	v_lshl_add_u64 v[34:35], v[34:35], 0, v[144:145]
	v_ashrrev_i32_e32 v33, 31, v32
	s_waitcnt vmcnt(1)
	v_lshlrev_b32_e32 v24, 16, v28
	v_and_b32_e32 v25, 0xffff0000, v28
	v_lshlrev_b32_e32 v26, 16, v29
	v_and_b32_e32 v27, 0xffff0000, v29
	v_lshlrev_b32_e32 v28, 16, v30
	v_and_b32_e32 v29, 0xffff0000, v30
	v_lshlrev_b32_e32 v30, 16, v31
	v_and_b32_e32 v31, 0xffff0000, v31
	v_pk_mul_f32 v[18:19], v[18:19], v[26:27]
	v_pk_mul_f32 v[16:17], v[16:17], v[24:25]
	v_pk_mul_f32 v[24:25], v[14:15], v[30:31]
	v_pk_mul_f32 v[14:15], v[12:13], v[28:29]
	v_cvt_pk_bf16_f32 v12, v16, v17
	v_cvt_pk_bf16_f32 v13, v18, v19
	s_nop 0
	v_cvt_pk_bf16_f32 v14, v14, v15
	v_cvt_pk_bf16_f32 v15, v24, v25
	global_load_dwordx4 v[16:19], v[34:35], off offset:1536 nt
	s_nop 0
	global_store_dwordx4 v[36:37], v[12:15], off offset:256
	s_waitcnt vmcnt(1)
	s_nop 0
	v_lshlrev_b32_e32 v12, 16, v16
	v_and_b32_e32 v13, 0xffff0000, v16
	v_lshlrev_b32_e32 v14, 16, v17
	v_and_b32_e32 v15, 0xffff0000, v17
	v_lshlrev_b32_e32 v16, 16, v18
	v_and_b32_e32 v17, 0xffff0000, v18
	v_lshlrev_b32_e32 v18, 16, v19
	v_and_b32_e32 v19, 0xffff0000, v19
	v_pk_mul_f32 v[14:15], v[22:23], v[14:15]
	v_pk_mul_f32 v[12:13], v[20:21], v[12:13]
	v_pk_mul_f32 v[18:19], v[10:11], v[18:19]
	v_pk_mul_f32 v[10:11], v[8:9], v[16:17]
	v_cvt_pk_bf16_f32 v8, v12, v13
	v_cvt_pk_bf16_f32 v9, v14, v15
	v_lshlrev_b64 v[16:17], 11, v[32:33]
	v_cvt_pk_bf16_f32 v10, v10, v11
	v_cvt_pk_bf16_f32 v11, v18, v19
	global_load_dwordx4 v[12:15], v[34:35], off offset:1792 nt
	v_lshl_add_u64 v[16:17], s[22:23], 0, v[16:17]
	v_lshl_add_u64 v[16:17], v[16:17], 0, v[144:145]
	global_store_dwordx4 v[16:17], v[8:11], off
	s_waitcnt vmcnt(1)
	s_nop 0
	v_lshlrev_b32_e32 v8, 16, v12
	v_and_b32_e32 v9, 0xffff0000, v12
	v_lshlrev_b32_e32 v10, 16, v13
	v_and_b32_e32 v11, 0xffff0000, v13
	v_lshlrev_b32_e32 v12, 16, v14
	v_and_b32_e32 v13, 0xffff0000, v14
	v_lshlrev_b32_e32 v14, 16, v15
	v_and_b32_e32 v15, 0xffff0000, v15
	v_pk_mul_f32 v[4:5], v[4:5], v[8:9]
	v_pk_mul_f32 v[8:9], v[2:3], v[14:15]
	v_pk_mul_f32 v[2:3], v[0:1], v[12:13]
	v_pk_mul_f32 v[6:7], v[6:7], v[10:11]
	v_cvt_pk_bf16_f32 v0, v4, v5
	s_nop 0
	v_cvt_pk_bf16_f32 v1, v6, v7
	v_cvt_pk_bf16_f32 v2, v2, v3
	v_cvt_pk_bf16_f32 v3, v8, v9
	global_store_dwordx4 v[16:17], v[0:3], off offset:256
	s_cbranch_vccnz .LBB0_635
	s_and_b64 vcc, exec, s[62:63]
	s_cbranch_vccnz .LBB0_634
	s_barrier
	s_branch .LBB0_634

; __device__ __forceinline__ unsigned cvt_pk_bf16(float lo, float hi) { unsigned r; asm volatile("v_cvt_pk_bf16_f32 %0, %1, %2" : "=v"(r) : "v"(lo), "v"(hi)); return r; }
;     __device__ __forceinline__ void operator()(const f32x4 (&acc)[2][2][4][2], const Unit& u, int wr, int wc, int fr, int fq) const {
;     ...
;         for (int ai = 0; ai < 2; ++ai)
; #pragma unroll
;             for (int m = 0; m < 4; ++m) {
;                 const size_t row = (size_t)(row0 + ai * HALF + m * 16);
; #pragma unroll
;                 for (int bj = 0; bj < 2; ++bj) {
;                     const int col = col0 + bj * HALF;
;                     f32x4 g0, g1; bf8(*(const u32x4*)(Q + row * QW + (MODE == 0 ? QC_GA : QC_GB) + col), g0, g1);
;                     f32x4 v0 = acc[ai][bj][m][0] * g0, v1 = acc[ai][bj][m][1] * g1;
;                     if (MODE == 1) { f32x4 t0, t1; bf8(*(const u32x4*)(merged + row * D + col), t0, t1); v0 += t0; v1 += t1; }
;                     u32x4 w; w.x = cvt_pk_bf16(v0[0], v0[1]); w.y = cvt_pk_bf16(v0[2], v0[3]); w.z = cvt_pk_bf16(v1[0], v1[1]); w.w = cvt_pk_bf16(v1[2], v1[3]);
;                     *(u32x4*)(merged + row * D + col) = w;
;                 }
.LBB0_666:
	v_lshl_add_u32 v146, s18, 8, v150
	v_lshl_add_u32 v144, s51, 8, v152
	v_ashrrev_i32_e32 v147, 31, v146
	v_readlane_b32 s22, v241, 19
	v_mov_b64_e32 v[148:149], s[60:61]
	v_ashrrev_i32_e32 v145, 31, v144
	v_lshlrev_b64 v[160:161], 11, v[146:147]
	v_readlane_b32 s23, v241, 20
	v_mad_i64_i32 v[156:157], s[20:21], v146, s50, v[148:149]
	v_lshlrev_b64 v[144:145], 1, v[144:145]
	v_lshl_add_u64 v[160:161], s[22:23], 0, v[160:161]
	v_lshl_add_u64 v[164:165], v[156:157], 0, v[144:145]
	v_lshl_add_u64 v[166:167], v[160:161], 0, v[144:145]
	global_load_dwordx4 v[156:159], v[164:165], off offset:3584 nt
	global_load_dwordx4 v[160:163], v[166:167], off nt
	s_andn2_b64 vcc, exec, s[0:1]
	s_mov_b64 s[0:1], -1
	s_waitcnt vmcnt(0)
	v_lshlrev_b32_e32 v168, 16, v156
	v_and_b32_e32 v169, 0xffff0000, v156
	v_lshlrev_b32_e32 v156, 16, v157
	v_and_b32_e32 v157, 0xffff0000, v157
	v_lshlrev_b32_e32 v170, 16, v158
	v_and_b32_e32 v171, 0xffff0000, v158
	v_lshlrev_b32_e32 v158, 16, v159
	v_and_b32_e32 v159, 0xffff0000, v159
	v_lshlrev_b32_e32 v172, 16, v160
	v_and_b32_e32 v173, 0xffff0000, v160
	v_lshlrev_b32_e32 v160, 16, v161
	v_and_b32_e32 v161, 0xffff0000, v161
	v_lshlrev_b32_e32 v174, 16, v162
	v_and_b32_e32 v175, 0xffff0000, v162
	v_lshlrev_b32_e32 v162, 16, v163
	v_and_b32_e32 v163, 0xffff0000, v163
	v_pk_fma_f32 v[126:127], v[126:127], v[156:157], v[160:161]
	v_pk_fma_f32 v[124:125], v[124:125], v[168:169], v[172:173]
	v_pk_fma_f32 v[156:157], v[122:123], v[158:159], v[162:163]
	v_pk_fma_f32 v[122:123], v[120:121], v[170:171], v[174:175]
	v_cvt_pk_bf16_f32 v120, v124, v125
	v_cvt_pk_bf16_f32 v121, v126, v127
	v_or_b32_e32 v160, 16, v146
	v_cvt_pk_bf16_f32 v122, v122, v123
	v_cvt_pk_bf16_f32 v123, v156, v157
	global_load_dwordx4 v[124:127], v[164:165], off offset:3840 nt
	global_load_dwordx4 v[156:159], v[166:167], off offset:256 nt
	v_ashrrev_i32_e32 v161, 31, v160
	global_store_dwordx4 v[166:167], v[120:123], off
	v_mad_i64_i32 v[162:163], s[20:21], v160, s50, v[148:149]
	v_lshl_add_u64 v[162:163], v[162:163], 0, v[144:145]
	s_waitcnt vmcnt(2)
	v_lshlrev_b32_e32 v120, 16, v124
	v_and_b32_e32 v121, 0xffff0000, v124
	v_lshlrev_b32_e32 v122, 16, v125
	v_and_b32_e32 v123, 0xffff0000, v125
	v_lshlrev_b32_e32 v124, 16, v126
	v_and_b32_e32 v125, 0xffff0000, v126
	v_lshlrev_b32_e32 v126, 16, v127
	v_and_b32_e32 v127, 0xffff0000, v127
	s_waitcnt vmcnt(1)
	v_lshlrev_b32_e32 v164, 16, v156
	v_and_b32_e32 v165, 0xffff0000, v156
	v_lshlrev_b32_e32 v168, 16, v158
	v_and_b32_e32 v169, 0xffff0000, v158
	v_lshlrev_b32_e32 v158, 16, v159
	v_and_b32_e32 v159, 0xffff0000, v159
	v_lshlrev_b32_e32 v156, 16, v157
	v_and_b32_e32 v157, 0xffff0000, v157
	v_pk_fma_f32 v[116:117], v[116:117], v[120:121], v[164:165]
	v_pk_fma_f32 v[120:121], v[114:115], v[126:127], v[158:159]
	v_pk_fma_f32 v[114:115], v[112:113], v[124:125], v[168:169]
	v_pk_fma_f32 v[118:119], v[118:119], v[122:123], v[156:157]
	v_cvt_pk_bf16_f32 v112, v116, v117
	s_nop 0
	v_cvt_pk_bf16_f32 v113, v118, v119
	v_cvt_pk_bf16_f32 v114, v114, v115
	v_cvt_pk_bf16_f32 v115, v120, v121
	v_lshlrev_b64 v[120:121], 11, v[160:161]
	v_lshl_add_u64 v[120:121], s[22:23], 0, v[120:121]
	v_lshl_add_u64 v[124:125], v[120:121], 0, v[144:145]
	global_load_dwordx4 v[116:119], v[162:163], off offset:3584 nt
	global_load_dwordx4 v[120:123], v[124:125], off nt
	s_waitcnt vmcnt(0)
	v_lshlrev_b32_e32 v126, 16, v120
	global_store_dwordx4 v[166:167], v[112:115], off offset:256
	v_and_b32_e32 v127, 0xffff0000, v120
	v_lshlrev_b32_e32 v120, 16, v121
	v_lshlrev_b32_e32 v112, 16, v116
	v_and_b32_e32 v113, 0xffff0000, v116
	v_lshlrev_b32_e32 v114, 16, v117
	v_and_b32_e32 v115, 0xffff0000, v117
	v_lshlrev_b32_e32 v116, 16, v118
	v_and_b32_e32 v117, 0xffff0000, v118
	v_lshlrev_b32_e32 v118, 16, v119
	v_and_b32_e32 v119, 0xffff0000, v119
	v_and_b32_e32 v121, 0xffff0000, v121
	v_lshlrev_b32_e32 v156, 16, v122
	v_and_b32_e32 v157, 0xffff0000, v122
	v_lshlrev_b32_e32 v122, 16, v123
	v_and_b32_e32 v123, 0xffff0000, v123
	v_pk_fma_f32 v[110:111], v[110:111], v[114:115], v[120:121]
	v_pk_fma_f32 v[108:109], v[108:109], v[112:113], v[126:127]
	v_pk_fma_f32 v[112:113], v[106:107], v[118:119], v[122:123]
	v_pk_fma_f32 v[106:107], v[104:105], v[116:117], v[156:157]
	v_cvt_pk_bf16_f32 v104, v108, v109
	v_cvt_pk_bf16_f32 v105, v110, v111
	v_or_b32_e32 v116, 32, v146
	v_cvt_pk_bf16_f32 v106, v106, v107
	v_cvt_pk_bf16_f32 v107, v112, v113
	global_load_dwordx4 v[108:111], v[162:163], off offset:3840 nt
	global_load_dwordx4 v[112:115], v[124:125], off offset:256 nt
	v_ashrrev_i32_e32 v117, 31, v116
	global_store_dwordx4 v[124:125], v[104:107], off
	v_mad_i64_i32 v[118:119], s[20:21], v116, s50, v[148:149]
	v_lshl_add_u64 v[118:119], v[118:119], 0, v[144:145]
	s_waitcnt vmcnt(2)
	v_lshlrev_b32_e32 v104, 16, v108
	v_and_b32_e32 v105, 0xffff0000, v108
	v_lshlrev_b32_e32 v106, 16, v109
	v_and_b32_e32 v107, 0xffff0000, v109
	v_lshlrev_b32_e32 v108, 16, v110
	v_and_b32_e32 v109, 0xffff0000, v110
	v_lshlrev_b32_e32 v110, 16, v111
	v_and_b32_e32 v111, 0xffff0000, v111
	s_waitcnt vmcnt(1)
	v_lshlrev_b32_e32 v120, 16, v112
	v_and_b32_e32 v121, 0xffff0000, v112
	v_lshlrev_b32_e32 v122, 16, v114
	v_and_b32_e32 v123, 0xffff0000, v114
	v_lshlrev_b32_e32 v114, 16, v115
	v_and_b32_e32 v115, 0xffff0000, v115
	v_lshlrev_b32_e32 v112, 16, v113
	v_and_b32_e32 v113, 0xffff0000, v113
	v_pk_fma_f32 v[100:101], v[100:101], v[104:105], v[120:121]
	v_pk_fma_f32 v[104:105], v[98:99], v[110:111], v[114:115]
	v_pk_fma_f32 v[98:99], v[96:97], v[108:109], v[122:123]
	v_pk_fma_f32 v[102:103], v[102:103], v[106:107], v[112:113]
	v_cvt_pk_bf16_f32 v96, v100, v101
	s_nop 0
	v_cvt_pk_bf16_f32 v97, v102, v103
	v_cvt_pk_bf16_f32 v98, v98, v99
	v_cvt_pk_bf16_f32 v99, v104, v105
	v_lshlrev_b64 v[104:105], 11, v[116:117]
	v_lshl_add_u64 v[104:105], s[22:23], 0, v[104:105]
	v_lshl_add_u64 v[108:109], v[104:105], 0, v[144:145]
	global_load_dwordx4 v[100:103], v[118:119], off offset:3584 nt
	global_load_dwordx4 v[104:107], v[108:109], off nt
	s_waitcnt vmcnt(0)
; __device__ __forceinline__ unsigned cvt_pk_bf16(float lo, float hi) { unsigned r; asm volatile("v_cvt_pk_bf16_f32 %0, %1, %2" : "=v"(r) : "v"(lo), "v"(hi)); return r; }
;     __device__ __forceinline__ void operator()(const f32x4 (&acc)[2][2][4][2], const Unit& u, int wr, int wc, int fr, int fq) const {
;     ...
;         for (int ai = 0; ai < 2; ++ai)
; #pragma unroll
;             for (int m = 0; m < 4; ++m) {
;                 const size_t row = (size_t)(row0 + ai * HALF + m * 16);
; #pragma unroll
;                 for (int bj = 0; bj < 2; ++bj) {
;                     const int col = col0 + bj * HALF;
;                     f32x4 g0, g1; bf8(*(const u32x4*)(Q + row * QW + (MODE == 0 ? QC_GA : QC_GB) + col), g0, g1);
;                     f32x4 v0 = acc[ai][bj][m][0] * g0, v1 = acc[ai][bj][m][1] * g1;
;                     if (MODE == 1) { f32x4 t0, t1; bf8(*(const u32x4*)(merged + row * D + col), t0, t1); v0 += t0; v1 += t1; }
;                     u32x4 w; w.x = cvt_pk_bf16(v0[0], v0[1]); w.y = cvt_pk_bf16(v0[2], v0[3]); w.z = cvt_pk_bf16(v1[0], v1[1]); w.w = cvt_pk_bf16(v1[2], v1[3]);
;                     *(u32x4*)(merged + row * D + col) = w;
;                 }
	v_lshlrev_b32_e32 v110, 16, v104
	global_store_dwordx4 v[124:125], v[96:99], off offset:256
	v_and_b32_e32 v111, 0xffff0000, v104
	v_lshlrev_b32_e32 v104, 16, v105
	v_lshlrev_b32_e32 v96, 16, v100
	v_and_b32_e32 v97, 0xffff0000, v100
	v_lshlrev_b32_e32 v98, 16, v101
	v_and_b32_e32 v99, 0xffff0000, v101
	v_lshlrev_b32_e32 v100, 16, v102
	v_and_b32_e32 v101, 0xffff0000, v102
	v_lshlrev_b32_e32 v102, 16, v103
	v_and_b32_e32 v103, 0xffff0000, v103
	v_and_b32_e32 v105, 0xffff0000, v105
	v_lshlrev_b32_e32 v112, 16, v106
	v_and_b32_e32 v113, 0xffff0000, v106
	v_lshlrev_b32_e32 v106, 16, v107
	v_and_b32_e32 v107, 0xffff0000, v107
	v_pk_fma_f32 v[94:95], v[94:95], v[98:99], v[104:105]
	v_pk_fma_f32 v[92:93], v[92:93], v[96:97], v[110:111]
	v_pk_fma_f32 v[96:97], v[90:91], v[102:103], v[106:107]
	v_pk_fma_f32 v[90:91], v[88:89], v[100:101], v[112:113]
	v_cvt_pk_bf16_f32 v88, v92, v93
	v_cvt_pk_bf16_f32 v89, v94, v95
	v_or_b32_e32 v100, 48, v146
	v_cvt_pk_bf16_f32 v90, v90, v91
	v_cvt_pk_bf16_f32 v91, v96, v97
	global_load_dwordx4 v[92:95], v[118:119], off offset:3840 nt
	global_load_dwordx4 v[96:99], v[108:109], off offset:256 nt
	v_ashrrev_i32_e32 v101, 31, v100
	global_store_dwordx4 v[108:109], v[88:91], off
	v_mad_i64_i32 v[102:103], s[20:21], v100, s50, v[148:149]
	v_lshl_add_u64 v[102:103], v[102:103], 0, v[144:145]
	s_waitcnt vmcnt(2)
	v_lshlrev_b32_e32 v88, 16, v92
	v_and_b32_e32 v89, 0xffff0000, v92
	v_lshlrev_b32_e32 v90, 16, v93
	v_and_b32_e32 v91, 0xffff0000, v93
	v_lshlrev_b32_e32 v92, 16, v94
	v_and_b32_e32 v93, 0xffff0000, v94
	v_lshlrev_b32_e32 v94, 16, v95
	v_and_b32_e32 v95, 0xffff0000, v95
	s_waitcnt vmcnt(1)
	v_lshlrev_b32_e32 v104, 16, v96
	v_and_b32_e32 v105, 0xffff0000, v96
	v_lshlrev_b32_e32 v106, 16, v98
	v_and_b32_e32 v107, 0xffff0000, v98
	v_lshlrev_b32_e32 v98, 16, v99
	v_and_b32_e32 v99, 0xffff0000, v99
	v_lshlrev_b32_e32 v96, 16, v97
	v_and_b32_e32 v97, 0xffff0000, v97
	v_pk_fma_f32 v[84:85], v[84:85], v[88:89], v[104:105]
	v_pk_fma_f32 v[88:89], v[82:83], v[94:95], v[98:99]
	v_pk_fma_f32 v[82:83], v[80:81], v[92:93], v[106:107]
	v_pk_fma_f32 v[86:87], v[86:87], v[90:91], v[96:97]
	v_cvt_pk_bf16_f32 v80, v84, v85
	s_nop 0
	v_cvt_pk_bf16_f32 v81, v86, v87
	v_cvt_pk_bf16_f32 v82, v82, v83
	v_cvt_pk_bf16_f32 v83, v88, v89
	v_lshlrev_b64 v[88:89], 11, v[100:101]
	v_lshl_add_u64 v[88:89], s[22:23], 0, v[88:89]
	v_lshl_add_u64 v[92:93], v[88:89], 0, v[144:145]
	global_load_dwordx4 v[84:87], v[102:103], off offset:3584 nt
	global_load_dwordx4 v[88:91], v[92:93], off nt
	s_waitcnt vmcnt(0)
	v_lshlrev_b32_e32 v94, 16, v88
	global_store_dwordx4 v[108:109], v[80:83], off offset:256
	v_and_b32_e32 v95, 0xffff0000, v88
	v_lshlrev_b32_e32 v88, 16, v89
	v_lshlrev_b32_e32 v80, 16, v84
	v_and_b32_e32 v81, 0xffff0000, v84
	v_lshlrev_b32_e32 v82, 16, v85
	v_and_b32_e32 v83, 0xffff0000, v85
	v_lshlrev_b32_e32 v84, 16, v86
	v_and_b32_e32 v85, 0xffff0000, v86
	v_lshlrev_b32_e32 v86, 16, v87
	v_and_b32_e32 v87, 0xffff0000, v87
	v_and_b32_e32 v89, 0xffff0000, v89
	v_lshlrev_b32_e32 v96, 16, v90
	v_and_b32_e32 v97, 0xffff0000, v90
	v_lshlrev_b32_e32 v90, 16, v91
	v_and_b32_e32 v91, 0xffff0000, v91
	v_pk_fma_f32 v[78:79], v[78:79], v[82:83], v[88:89]
	v_pk_fma_f32 v[76:77], v[76:77], v[80:81], v[94:95]
	v_pk_fma_f32 v[80:81], v[74:75], v[86:87], v[90:91]
	v_pk_fma_f32 v[74:75], v[72:73], v[84:85], v[96:97]
	v_cvt_pk_bf16_f32 v72, v76, v77
	v_cvt_pk_bf16_f32 v73, v78, v79
	v_add_u32_e32 v84, 0x80, v146
	v_cvt_pk_bf16_f32 v74, v74, v75
	v_cvt_pk_bf16_f32 v75, v80, v81
	global_load_dwordx4 v[76:79], v[102:103], off offset:3840 nt
	global_load_dwordx4 v[80:83], v[92:93], off offset:256 nt
	v_ashrrev_i32_e32 v85, 31, v84
	global_store_dwordx4 v[92:93], v[72:75], off
	v_mad_i64_i32 v[86:87], s[20:21], v84, s50, v[148:149]
	v_lshl_add_u64 v[86:87], v[86:87], 0, v[144:145]
	s_waitcnt vmcnt(2)
	v_lshlrev_b32_e32 v72, 16, v76
	v_and_b32_e32 v73, 0xffff0000, v76
	v_lshlrev_b32_e32 v74, 16, v77
	v_and_b32_e32 v75, 0xffff0000, v77
	v_lshlrev_b32_e32 v76, 16, v78
	v_and_b32_e32 v77, 0xffff0000, v78
	v_lshlrev_b32_e32 v78, 16, v79
	v_and_b32_e32 v79, 0xffff0000, v79
	s_waitcnt vmcnt(1)
	v_lshlrev_b32_e32 v88, 16, v80
	v_and_b32_e32 v89, 0xffff0000, v80
	v_lshlrev_b32_e32 v90, 16, v82
	v_and_b32_e32 v91, 0xffff0000, v82
	v_lshlrev_b32_e32 v82, 16, v83
	v_and_b32_e32 v83, 0xffff0000, v83
	v_lshlrev_b32_e32 v80, 16, v81
	v_and_b32_e32 v81, 0xffff0000, v81
	v_pk_fma_f32 v[68:69], v[68:69], v[72:73], v[88:89]
	v_pk_fma_f32 v[72:73], v[66:67], v[78:79], v[82:83]
	v_pk_fma_f32 v[66:67], v[64:65], v[76:77], v[90:91]
	v_pk_fma_f32 v[70:71], v[70:71], v[74:75], v[80:81]
	v_cvt_pk_bf16_f32 v64, v68, v69
	s_nop 0
	v_cvt_pk_bf16_f32 v65, v70, v71
	v_cvt_pk_bf16_f32 v66, v66, v67
	v_cvt_pk_bf16_f32 v67, v72, v73
	v_lshlrev_b64 v[72:73], 11, v[84:85]
	v_lshl_add_u64 v[72:73], s[22:23], 0, v[72:73]
	v_lshl_add_u64 v[76:77], v[72:73], 0, v[144:145]
	global_load_dwordx4 v[68:71], v[86:87], off offset:3584 nt
	global_load_dwordx4 v[72:75], v[76:77], off nt
	s_waitcnt vmcnt(0)
; __device__ __forceinline__ unsigned cvt_pk_bf16(float lo, float hi) { unsigned r; asm volatile("v_cvt_pk_bf16_f32 %0, %1, %2" : "=v"(r) : "v"(lo), "v"(hi)); return r; }
;     __device__ __forceinline__ void operator()(const f32x4 (&acc)[2][2][4][2], const Unit& u, int wr, int wc, int fr, int fq) const {
;     ...
;         for (int ai = 0; ai < 2; ++ai)
; #pragma unroll
;             for (int m = 0; m < 4; ++m) {
;                 const size_t row = (size_t)(row0 + ai * HALF + m * 16);
; #pragma unroll
;                 for (int bj = 0; bj < 2; ++bj) {
;                     const int col = col0 + bj * HALF;
;                     f32x4 g0, g1; bf8(*(const u32x4*)(Q + row * QW + (MODE == 0 ? QC_GA : QC_GB) + col), g0, g1);
;                     f32x4 v0 = acc[ai][bj][m][0] * g0, v1 = acc[ai][bj][m][1] * g1;
;                     if (MODE == 1) { f32x4 t0, t1; bf8(*(const u32x4*)(merged + row * D + col), t0, t1); v0 += t0; v1 += t1; }
;                     u32x4 w; w.x = cvt_pk_bf16(v0[0], v0[1]); w.y = cvt_pk_bf16(v0[2], v0[3]); w.z = cvt_pk_bf16(v1[0], v1[1]); w.w = cvt_pk_bf16(v1[2], v1[3]);
;                     *(u32x4*)(merged + row * D + col) = w;
;                 }
	v_lshlrev_b32_e32 v78, 16, v72
	global_store_dwordx4 v[92:93], v[64:67], off offset:256
	v_and_b32_e32 v79, 0xffff0000, v72
	v_lshlrev_b32_e32 v72, 16, v73
	v_lshlrev_b32_e32 v64, 16, v68
	v_and_b32_e32 v65, 0xffff0000, v68
	v_lshlrev_b32_e32 v66, 16, v69
	v_and_b32_e32 v67, 0xffff0000, v69
	v_lshlrev_b32_e32 v68, 16, v70
	v_and_b32_e32 v69, 0xffff0000, v70
	v_lshlrev_b32_e32 v70, 16, v71
	v_and_b32_e32 v71, 0xffff0000, v71
	v_and_b32_e32 v73, 0xffff0000, v73
	v_lshlrev_b32_e32 v80, 16, v74
	v_and_b32_e32 v81, 0xffff0000, v74
	v_lshlrev_b32_e32 v74, 16, v75
	v_and_b32_e32 v75, 0xffff0000, v75
	v_pk_fma_f32 v[62:63], v[62:63], v[66:67], v[72:73]
	v_pk_fma_f32 v[60:61], v[60:61], v[64:65], v[78:79]
	v_pk_fma_f32 v[64:65], v[58:59], v[70:71], v[74:75]
	v_pk_fma_f32 v[58:59], v[56:57], v[68:69], v[80:81]
	v_cvt_pk_bf16_f32 v56, v60, v61
	v_cvt_pk_bf16_f32 v57, v62, v63
	v_add_u32_e32 v68, 0x90, v146
	v_cvt_pk_bf16_f32 v58, v58, v59
	v_cvt_pk_bf16_f32 v59, v64, v65
	global_load_dwordx4 v[60:63], v[86:87], off offset:3840 nt
	global_load_dwordx4 v[64:67], v[76:77], off offset:256 nt
	v_ashrrev_i32_e32 v69, 31, v68
	global_store_dwordx4 v[76:77], v[56:59], off
	v_mad_i64_i32 v[70:71], s[20:21], v68, s50, v[148:149]
	v_lshl_add_u64 v[70:71], v[70:71], 0, v[144:145]
	s_waitcnt vmcnt(2)
	v_lshlrev_b32_e32 v56, 16, v60
	v_and_b32_e32 v57, 0xffff0000, v60
	v_lshlrev_b32_e32 v58, 16, v61
	v_and_b32_e32 v59, 0xffff0000, v61
	v_lshlrev_b32_e32 v60, 16, v62
	v_and_b32_e32 v61, 0xffff0000, v62
	v_lshlrev_b32_e32 v62, 16, v63
	v_and_b32_e32 v63, 0xffff0000, v63
	s_waitcnt vmcnt(1)
	v_lshlrev_b32_e32 v72, 16, v64
	v_and_b32_e32 v73, 0xffff0000, v64
	v_lshlrev_b32_e32 v74, 16, v66
	v_and_b32_e32 v75, 0xffff0000, v66
	v_lshlrev_b32_e32 v66, 16, v67
	v_and_b32_e32 v67, 0xffff0000, v67
	v_lshlrev_b32_e32 v64, 16, v65
	v_and_b32_e32 v65, 0xffff0000, v65
	v_pk_fma_f32 v[52:53], v[52:53], v[56:57], v[72:73]
	v_pk_fma_f32 v[56:57], v[50:51], v[62:63], v[66:67]
	v_pk_fma_f32 v[50:51], v[48:49], v[60:61], v[74:75]
	v_pk_fma_f32 v[54:55], v[54:55], v[58:59], v[64:65]
	v_cvt_pk_bf16_f32 v48, v52, v53
	s_nop 0
	v_cvt_pk_bf16_f32 v49, v54, v55
	v_cvt_pk_bf16_f32 v50, v50, v51
	v_cvt_pk_bf16_f32 v51, v56, v57
	v_lshlrev_b64 v[56:57], 11, v[68:69]
	v_lshl_add_u64 v[56:57], s[22:23], 0, v[56:57]
	v_lshl_add_u64 v[60:61], v[56:57], 0, v[144:145]
	global_load_dwordx4 v[52:55], v[70:71], off offset:3584 nt
	global_load_dwordx4 v[56:59], v[60:61], off nt
	s_waitcnt vmcnt(0)
	v_lshlrev_b32_e32 v62, 16, v56
	global_store_dwordx4 v[76:77], v[48:51], off offset:256
	v_and_b32_e32 v63, 0xffff0000, v56
	v_lshlrev_b32_e32 v56, 16, v57
	v_lshlrev_b32_e32 v48, 16, v52
	v_and_b32_e32 v49, 0xffff0000, v52
	v_lshlrev_b32_e32 v50, 16, v53
	v_and_b32_e32 v51, 0xffff0000, v53
	v_lshlrev_b32_e32 v52, 16, v54
	v_and_b32_e32 v53, 0xffff0000, v54
	v_lshlrev_b32_e32 v54, 16, v55
	v_and_b32_e32 v55, 0xffff0000, v55
	v_and_b32_e32 v57, 0xffff0000, v57
	v_lshlrev_b32_e32 v64, 16, v58
	v_and_b32_e32 v65, 0xffff0000, v58
	v_lshlrev_b32_e32 v58, 16, v59
	v_and_b32_e32 v59, 0xffff0000, v59
	v_pk_fma_f32 v[46:47], v[46:47], v[50:51], v[56:57]
	v_pk_fma_f32 v[44:45], v[44:45], v[48:49], v[62:63]
	v_pk_fma_f32 v[48:49], v[42:43], v[54:55], v[58:59]
	v_pk_fma_f32 v[42:43], v[40:41], v[52:53], v[64:65]
	v_cvt_pk_bf16_f32 v40, v44, v45
	v_cvt_pk_bf16_f32 v41, v46, v47
	v_add_u32_e32 v52, 0xa0, v146
	v_cvt_pk_bf16_f32 v42, v42, v43
	v_cvt_pk_bf16_f32 v43, v48, v49
	global_load_dwordx4 v[44:47], v[70:71], off offset:3840 nt
	global_load_dwordx4 v[48:51], v[60:61], off offset:256 nt
	v_ashrrev_i32_e32 v53, 31, v52
	global_store_dwordx4 v[60:61], v[40:43], off
	v_mad_i64_i32 v[54:55], s[20:21], v52, s50, v[148:149]
	v_lshl_add_u64 v[54:55], v[54:55], 0, v[144:145]
	s_waitcnt vmcnt(2)
	v_lshlrev_b32_e32 v40, 16, v44
	v_and_b32_e32 v41, 0xffff0000, v44
	v_lshlrev_b32_e32 v42, 16, v45
	v_and_b32_e32 v43, 0xffff0000, v45
	v_lshlrev_b32_e32 v44, 16, v46
	v_and_b32_e32 v45, 0xffff0000, v46
	v_lshlrev_b32_e32 v46, 16, v47
	v_and_b32_e32 v47, 0xffff0000, v47
	s_waitcnt vmcnt(1)
	v_lshlrev_b32_e32 v56, 16, v48
	v_and_b32_e32 v57, 0xffff0000, v48
	v_lshlrev_b32_e32 v58, 16, v50
	v_and_b32_e32 v59, 0xffff0000, v50
	v_lshlrev_b32_e32 v50, 16, v51
	v_and_b32_e32 v51, 0xffff0000, v51
	v_lshlrev_b32_e32 v48, 16, v49
	v_and_b32_e32 v49, 0xffff0000, v49
	v_pk_fma_f32 v[36:37], v[36:37], v[40:41], v[56:57]
	v_pk_fma_f32 v[40:41], v[34:35], v[46:47], v[50:51]
	v_pk_fma_f32 v[34:35], v[32:33], v[44:45], v[58:59]
	v_pk_fma_f32 v[38:39], v[38:39], v[42:43], v[48:49]
	v_cvt_pk_bf16_f32 v32, v36, v37
	s_nop 0
	v_cvt_pk_bf16_f32 v33, v38, v39
	v_cvt_pk_bf16_f32 v34, v34, v35
	v_cvt_pk_bf16_f32 v35, v40, v41
	v_lshlrev_b64 v[40:41], 11, v[52:53]
	v_lshl_add_u64 v[40:41], s[22:23], 0, v[40:41]
	v_lshl_add_u64 v[44:45], v[40:41], 0, v[144:145]
	global_load_dwordx4 v[36:39], v[54:55], off offset:3584 nt
	global_load_dwordx4 v[40:43], v[44:45], off nt
	s_waitcnt vmcnt(0)
; __device__ __forceinline__ unsigned cvt_pk_bf16(float lo, float hi) { unsigned r; asm volatile("v_cvt_pk_bf16_f32 %0, %1, %2" : "=v"(r) : "v"(lo), "v"(hi)); return r; }
;     __device__ __forceinline__ void operator()(const f32x4 (&acc)[2][2][4][2], const Unit& u, int wr, int wc, int fr, int fq) const {
;     ...
;         for (int ai = 0; ai < 2; ++ai)
; #pragma unroll
;             for (int m = 0; m < 4; ++m) {
;                 const size_t row = (size_t)(row0 + ai * HALF + m * 16);
; #pragma unroll
;                 for (int bj = 0; bj < 2; ++bj) {
;                     const int col = col0 + bj * HALF;
;                     f32x4 g0, g1; bf8(*(const u32x4*)(Q + row * QW + (MODE == 0 ? QC_GA : QC_GB) + col), g0, g1);
;                     f32x4 v0 = acc[ai][bj][m][0] * g0, v1 = acc[ai][bj][m][1] * g1;
;                     if (MODE == 1) { f32x4 t0, t1; bf8(*(const u32x4*)(merged + row * D + col), t0, t1); v0 += t0; v1 += t1; }
;                     u32x4 w; w.x = cvt_pk_bf16(v0[0], v0[1]); w.y = cvt_pk_bf16(v0[2], v0[3]); w.z = cvt_pk_bf16(v1[0], v1[1]); w.w = cvt_pk_bf16(v1[2], v1[3]);
;                     *(u32x4*)(merged + row * D + col) = w;
;                 }
	v_lshlrev_b32_e32 v46, 16, v40
	global_store_dwordx4 v[60:61], v[32:35], off offset:256
	v_and_b32_e32 v47, 0xffff0000, v40
	v_lshlrev_b32_e32 v40, 16, v41
	v_lshlrev_b32_e32 v32, 16, v36
	v_and_b32_e32 v33, 0xffff0000, v36
	v_lshlrev_b32_e32 v34, 16, v37
	v_and_b32_e32 v35, 0xffff0000, v37
	v_lshlrev_b32_e32 v36, 16, v38
	v_and_b32_e32 v37, 0xffff0000, v38
	v_lshlrev_b32_e32 v38, 16, v39
	v_and_b32_e32 v39, 0xffff0000, v39
	v_and_b32_e32 v41, 0xffff0000, v41
	v_lshlrev_b32_e32 v48, 16, v42
	v_and_b32_e32 v49, 0xffff0000, v42
	v_lshlrev_b32_e32 v42, 16, v43
	v_and_b32_e32 v43, 0xffff0000, v43
	v_pk_fma_f32 v[30:31], v[30:31], v[34:35], v[40:41]
	v_pk_fma_f32 v[28:29], v[28:29], v[32:33], v[46:47]
	v_pk_fma_f32 v[32:33], v[26:27], v[38:39], v[42:43]
	v_pk_fma_f32 v[26:27], v[24:25], v[36:37], v[48:49]
	v_cvt_pk_bf16_f32 v24, v28, v29
	v_cvt_pk_bf16_f32 v25, v30, v31
	v_add_u32_e32 v36, 0xb0, v146
	v_cvt_pk_bf16_f32 v26, v26, v27
	v_cvt_pk_bf16_f32 v27, v32, v33
	global_load_dwordx4 v[28:31], v[54:55], off offset:3840 nt
	global_load_dwordx4 v[32:35], v[44:45], off offset:256 nt
	v_ashrrev_i32_e32 v37, 31, v36
	global_store_dwordx4 v[44:45], v[24:27], off
	v_mad_i64_i32 v[38:39], s[20:21], v36, s50, v[148:149]
	v_lshl_add_u64 v[38:39], v[38:39], 0, v[144:145]
	s_waitcnt vmcnt(2)
	v_lshlrev_b32_e32 v24, 16, v28
	v_and_b32_e32 v25, 0xffff0000, v28
	v_lshlrev_b32_e32 v26, 16, v29
	v_and_b32_e32 v27, 0xffff0000, v29
	v_lshlrev_b32_e32 v28, 16, v30
	v_and_b32_e32 v29, 0xffff0000, v30
	v_lshlrev_b32_e32 v30, 16, v31
	v_and_b32_e32 v31, 0xffff0000, v31
	s_waitcnt vmcnt(1)
	v_lshlrev_b32_e32 v40, 16, v32
	v_and_b32_e32 v41, 0xffff0000, v32
	v_lshlrev_b32_e32 v42, 16, v34
	v_and_b32_e32 v43, 0xffff0000, v34
	v_lshlrev_b32_e32 v34, 16, v35
	v_and_b32_e32 v35, 0xffff0000, v35
	v_lshlrev_b32_e32 v32, 16, v33
	v_and_b32_e32 v33, 0xffff0000, v33
	v_pk_fma_f32 v[20:21], v[20:21], v[24:25], v[40:41]
	v_pk_fma_f32 v[24:25], v[18:19], v[30:31], v[34:35]
	v_pk_fma_f32 v[18:19], v[16:17], v[28:29], v[42:43]
	v_pk_fma_f32 v[22:23], v[22:23], v[26:27], v[32:33]
	v_cvt_pk_bf16_f32 v16, v20, v21
	s_nop 0
	v_cvt_pk_bf16_f32 v17, v22, v23
	v_cvt_pk_bf16_f32 v18, v18, v19
	v_cvt_pk_bf16_f32 v19, v24, v25
	v_lshlrev_b64 v[24:25], 11, v[36:37]
	v_lshl_add_u64 v[24:25], s[22:23], 0, v[24:25]
	v_lshl_add_u64 v[28:29], v[24:25], 0, v[144:145]
	global_load_dwordx4 v[20:23], v[38:39], off offset:3584 nt
	global_load_dwordx4 v[24:27], v[28:29], off nt
	s_waitcnt vmcnt(0)
	v_lshlrev_b32_e32 v30, 16, v24
	global_store_dwordx4 v[44:45], v[16:19], off offset:256
	v_and_b32_e32 v31, 0xffff0000, v24
	v_lshlrev_b32_e32 v24, 16, v25
	v_lshlrev_b32_e32 v16, 16, v20
	v_and_b32_e32 v17, 0xffff0000, v20
	v_lshlrev_b32_e32 v18, 16, v21
	v_and_b32_e32 v19, 0xffff0000, v21
	v_lshlrev_b32_e32 v20, 16, v22
	v_and_b32_e32 v21, 0xffff0000, v22
	v_lshlrev_b32_e32 v22, 16, v23
	v_and_b32_e32 v23, 0xffff0000, v23
	v_and_b32_e32 v25, 0xffff0000, v25
	v_lshlrev_b32_e32 v32, 16, v26
	v_and_b32_e32 v33, 0xffff0000, v26
	v_lshlrev_b32_e32 v26, 16, v27
	v_and_b32_e32 v27, 0xffff0000, v27
	v_pk_fma_f32 v[14:15], v[14:15], v[18:19], v[24:25]
	v_pk_fma_f32 v[12:13], v[12:13], v[16:17], v[30:31]
	v_pk_fma_f32 v[16:17], v[10:11], v[22:23], v[26:27]
	v_pk_fma_f32 v[10:11], v[8:9], v[20:21], v[32:33]
	v_cvt_pk_bf16_f32 v8, v12, v13
	v_cvt_pk_bf16_f32 v9, v14, v15
	s_nop 0
	v_cvt_pk_bf16_f32 v10, v10, v11
	v_cvt_pk_bf16_f32 v11, v16, v17
	global_load_dwordx4 v[12:15], v[38:39], off offset:3840 nt
	global_load_dwordx4 v[16:19], v[28:29], off offset:256 nt
	s_waitcnt vmcnt(0)
	v_lshlrev_b32_e32 v20, 16, v16
	global_store_dwordx4 v[28:29], v[8:11], off
	v_and_b32_e32 v21, 0xffff0000, v16
	v_lshlrev_b32_e32 v22, 16, v18
	v_lshlrev_b32_e32 v8, 16, v12
	v_and_b32_e32 v9, 0xffff0000, v12
	v_lshlrev_b32_e32 v10, 16, v13
	v_and_b32_e32 v11, 0xffff0000, v13
	v_lshlrev_b32_e32 v12, 16, v14
	v_and_b32_e32 v13, 0xffff0000, v14
	v_lshlrev_b32_e32 v14, 16, v15
	v_and_b32_e32 v15, 0xffff0000, v15
	v_and_b32_e32 v23, 0xffff0000, v18
	v_lshlrev_b32_e32 v18, 16, v19
	v_and_b32_e32 v19, 0xffff0000, v19
	v_lshlrev_b32_e32 v16, 16, v17
	v_and_b32_e32 v17, 0xffff0000, v17
	v_pk_fma_f32 v[4:5], v[4:5], v[8:9], v[20:21]
	v_pk_fma_f32 v[8:9], v[2:3], v[14:15], v[18:19]
	v_pk_fma_f32 v[2:3], v[0:1], v[12:13], v[22:23]
	v_pk_fma_f32 v[6:7], v[6:7], v[10:11], v[16:17]
	v_cvt_pk_bf16_f32 v0, v4, v5
	s_nop 0
	v_cvt_pk_bf16_f32 v1, v6, v7
	v_cvt_pk_bf16_f32 v2, v2, v3
	v_cvt_pk_bf16_f32 v3, v8, v9
	global_store_dwordx4 v[28:29], v[0:3], off offset:256
	s_cbranch_vccnz .LBB0_655
	s_and_b64 vcc, exec, s[62:63]
	s_cbranch_vccnz .LBB0_654
	s_barrier
	s_branch .LBB0_654
